# RWKV prep: lora weight loads of a head issued together (one wait), parameter rows loaded together at task start
# baseline (speedup 1.0000x reference)
.LBB0_1754:
	s_mov_b64 s[0:1], 0
	v_mov_b32_e32 v2, v191
	v_mov_b32_e32 v3, v190
	v_mov_b32_e32 v4, v153
	s_waitcnt vmcnt(0)
	s_barrier
	v_lshl_add_u64 v[0:1], s[64:65], 0, v[116:117]
	global_load_dword v4, v[0:1], off
	v_lshl_add_u64 v[0:1], s[68:69], 0, v[116:117]
	global_load_dword v5, v[0:1], off
	v_lshl_add_u64 v[0:1], s[72:73], 0, v[116:117]
	global_load_dword v6, v[0:1], off
	v_lshl_add_u64 v[0:1], s[74:75], 0, v[116:117]
	global_load_dword v7, v[0:1], off
	global_load_dword v8, v[134:135], off
	global_load_dword v9, v[134:135], off offset:2048
	v_lshl_add_u64 v[0:1], v[134:135], 0, s[10:11]
	v_lshl_add_u64 v[0:1], v[0:1], 0, s[10:11]
	global_load_dword v10, v[0:1], off
	v_cmp_gt_u32_e32 vcc, 0x100, v153
	s_and_saveexec_b64 s[0:1], vcc
	global_load_dword v11, v[0:1], off offset:2048
	s_mov_b64 exec, s[0:1]
	s_waitcnt vmcnt(0)
	ds_write_b32 v190, v4
	ds_write_b32 v190, v5 offset:2048
	ds_write_b32 v190, v6 offset:4096
	ds_write_b32 v190, v7 offset:6144
	ds_write_b32 v192, v8
	ds_write_b32 v192, v9 offset:2048
	ds_write_b32 v192, v10 offset:4096
	s_and_saveexec_b64 s[0:1], vcc
	ds_write_b32 v192, v11 offset:6144
	s_mov_b64 exec, s[0:1]
	s_mov_b64 s[0:1], 0
	s_or_b64 exec, exec, s[0:1]
	v_lshl_add_u32 v10, s40, 7, v188
	v_mov_b64_e32 v[0:1], s[6:7]
	v_mad_i64_i32 v[2:3], s[0:1], v10, s26, v[0:1]
	v_and_b32_e32 v0, 0x7ff, v10
	v_cmp_eq_u32_e64 s[2:3], 0, v0
	v_mov_b32_e32 v157, v117
	v_lshl_add_u64 v[4:5], v[2:3], 0, v[156:157]
	v_cndmask_b32_e64 v1, -1, 0, s[2:3]
	v_cndmask_b32_e64 v0, v203, 0, s[2:3]
	v_lshl_add_u64 v[2:3], v[2:3], 0, v[0:1]
	global_load_dwordx4 v[6:9], v[4:5], off offset:3072
	v_lshl_add_u64 v[2:3], v[2:3], 0, v[156:157]
	global_load_dwordx4 v[10:13], v[2:3], off offset:3072
	global_load_dwordx4 v[14:17], v[118:119], off
	global_load_dwordx4 v[18:21], v[118:119], off offset:16
	v_ashrrev_i32_e32 v141, 31, v140
	v_lshlrev_b64 v[30:31], 10, v[140:141]
	global_load_dwordx4 v[22:25], v[120:121], off offset:16
	global_load_dwordx4 v[26:29], v[120:121], off
	v_lshl_add_u64 v[160:161], v[138:139], 0, v[30:31]
	v_lshl_add_u64 v[162:163], v[150:151], 0, v[30:31]
	global_load_dwordx4 v[30:33], v[4:5], off offset:3136
	global_load_dwordx4 v[34:37], v[2:3], off offset:3136
	v_mad_i64_i32 v[0:1], s[0:1], v140, s26, v[0:1]
	v_mad_i64_i32 v[158:159], s[0:1], v140, s26, v[138:139]
	v_lshl_add_u64 v[164:165], v[154:155], 0, v[0:1]
	s_mov_b64 s[16:17], 0
	v_mov_b32_e32 v141, v193
	v_mov_b64_e32 v[166:167], v[148:149]
	v_mov_b64_e32 v[168:169], v[146:147]
	v_mov_b64_e32 v[170:171], v[144:145]
	v_mov_b64_e32 v[172:173], v[142:143]
	v_mov_b64_e32 v[174:175], v[136:137]
	s_waitcnt vmcnt(7)
	v_lshlrev_b32_e32 v39, 16, v7
	s_waitcnt vmcnt(6)
	v_lshlrev_b32_e32 v43, 16, v11
	v_lshlrev_b32_e32 v44, 16, v12
	v_lshlrev_b32_e32 v40, 16, v8
	v_lshlrev_b32_e32 v41, 16, v9
	v_and_b32_e32 v42, 0xffff0000, v9
	v_lshlrev_b32_e32 v9, 16, v10
	v_and_b32_e32 v10, 0xffff0000, v10
	v_and_b32_e32 v11, 0xffff0000, v11
	v_and_b32_e32 v12, 0xffff0000, v12
	v_cndmask_b32_e64 v44, v44, 0, s[2:3]
	v_cndmask_b32_e64 v43, v43, 0, s[2:3]
	v_lshlrev_b32_e32 v38, 16, v6
	v_and_b32_e32 v6, 0xffff0000, v6
	v_and_b32_e32 v7, 0xffff0000, v7
	v_and_b32_e32 v8, 0xffff0000, v8
	v_cndmask_b32_e64 v10, v10, 0, s[2:3]
	v_cndmask_b32_e64 v12, v12, 0, s[2:3]
	v_cndmask_b32_e64 v11, v11, 0, s[2:3]
	v_sub_f32_e32 v44, v44, v40
	v_sub_f32_e32 v43, v43, v39
	v_sub_f32_e32 v10, v10, v6
	v_sub_f32_e32 v12, v12, v8
	v_sub_f32_e32 v11, v11, v7
	s_waitcnt vmcnt(4)
	v_fmac_f32_e32 v40, v18, v44
	v_fmac_f32_e32 v39, v16, v43
	v_fmac_f32_e32 v6, v15, v10
	v_fmac_f32_e32 v8, v19, v12
	v_fmac_f32_e32 v7, v17, v11
	v_add_f32_e32 v10, v39, v39
	v_add_f32_e32 v11, v40, v40
	v_add_f32_e32 v8, v8, v8
	v_mul_f32_e32 v10, 0x3fb8aa3b, v10
	v_mul_f32_e32 v11, 0x3fb8aa3b, v11
	v_add_f32_e32 v6, v6, v6
	v_mul_f32_e32 v8, 0x3fb8aa3b, v8
	v_exp_f32_e32 v10, v10
	v_exp_f32_e32 v11, v11
	v_lshlrev_b32_e32 v45, 16, v13
	v_and_b32_e32 v13, 0xffff0000, v13
	v_add_f32_e32 v7, v7, v7
	v_mul_f32_e32 v6, 0x3fb8aa3b, v6
	v_exp_f32_e32 v8, v8
	v_cndmask_b32_e64 v9, v9, 0, s[2:3]
	v_cndmask_b32_e64 v45, v45, 0, s[2:3]
	v_cndmask_b32_e64 v13, v13, 0, s[2:3]
	v_mul_f32_e32 v7, 0x3fb8aa3b, v7
	v_exp_f32_e32 v6, v6
	v_sub_f32_e32 v9, v9, v38
	v_sub_f32_e32 v45, v45, v41
	v_sub_f32_e32 v13, v13, v42
	v_exp_f32_e32 v7, v7
	v_fmac_f32_e32 v38, v14, v9
	v_fmac_f32_e32 v41, v20, v45
	v_fmac_f32_e32 v42, v21, v13
	v_add_f32_e32 v10, 1.0, v10
	v_add_f32_e32 v11, 1.0, v11
	v_add_f32_e32 v9, v38, v38
	v_add_f32_e32 v12, v41, v41
	v_add_f32_e32 v15, 1.0, v8
	v_rcp_f32_e32 v8, v10
	v_rcp_f32_e32 v10, v11
	v_add_f32_e32 v11, v42, v42
	v_mul_f32_e32 v9, 0x3fb8aa3b, v9
	v_mul_f32_e32 v12, 0x3fb8aa3b, v12
	v_add_f32_e32 v13, 1.0, v6
	v_mul_f32_e32 v11, 0x3fb8aa3b, v11
	v_exp_f32_e32 v9, v9
	v_exp_f32_e32 v12, v12
	v_add_f32_e32 v14, 1.0, v7
	v_rcp_f32_e32 v7, v13
	v_exp_f32_e32 v13, v11
	v_add_f32_e32 v9, 1.0, v9
	v_add_f32_e32 v12, 1.0, v12
	v_rcp_f32_e32 v6, v9
	v_add_f32_e32 v13, 1.0, v13
	v_rcp_f32_e32 v9, v14
	v_rcp_f32_e32 v11, v15
	v_rcp_f32_e32 v12, v12
	v_rcp_f32_e32 v13, v13
	v_pk_fma_f32 v[6:7], v[6:7], 2.0, 1.0 op_sel_hi:[1,0,0] neg_lo:[1,0,0] neg_hi:[1,0,0]
	v_pk_fma_f32 v[8:9], v[8:9], 2.0, 1.0 op_sel_hi:[1,0,0] neg_lo:[1,0,0] neg_hi:[1,0,0]
	v_pk_fma_f32 v[10:11], v[10:11], 2.0, 1.0 op_sel_hi:[1,0,0] neg_lo:[1,0,0] neg_hi:[1,0,0]
	v_pk_fma_f32 v[12:13], v[12:13], 2.0, 1.0 op_sel_hi:[1,0,0] neg_lo:[1,0,0] neg_hi:[1,0,0]
	v_cvt_pk_bf16_f32 v6, v6, v7
	v_cvt_pk_bf16_f32 v7, v8, v9
	v_cvt_pk_bf16_f32 v8, v10, v11
	v_cvt_pk_bf16_f32 v9, v12, v13
	ds_write_b128 v204, v[6:9] offset:52224
	s_waitcnt vmcnt(0)
	v_lshlrev_b32_e32 v6, 16, v34
	v_lshlrev_b32_e32 v14, 16, v35
	v_lshlrev_b32_e32 v38, 16, v30
	v_lshlrev_b32_e32 v39, 16, v31
	v_and_b32_e32 v10, 0xffff0000, v34
	v_lshlrev_b32_e32 v11, 16, v36
	v_lshlrev_b32_e32 v15, 16, v37
	v_cndmask_b32_e64 v13, v6, 0, s[2:3]
	v_cndmask_b32_e64 v14, v14, 0, s[2:3]
	v_and_b32_e32 v30, 0xffff0000, v30
	v_lshlrev_b32_e32 v41, 16, v32
	v_lshlrev_b32_e32 v42, 16, v33
	v_and_b32_e32 v12, 0xffff0000, v36
	v_cndmask_b32_e64 v11, v11, 0, s[2:3]
	v_sub_f32_e32 v13, v13, v38
	v_cndmask_b32_e64 v16, v10, 0, s[2:3]
	v_cndmask_b32_e64 v15, v15, 0, s[2:3]
	v_sub_f32_e32 v14, v14, v39
	v_and_b32_e32 v32, 0xffff0000, v32
	v_and_b32_e32 v34, 0xffff0000, v35
	v_fmac_f32_e32 v38, v26, v13
	v_sub_f32_e32 v11, v11, v41
	v_cndmask_b32_e64 v17, v12, 0, s[2:3]
	v_sub_f32_e32 v16, v16, v30
	v_fmac_f32_e32 v39, v28, v14
	v_sub_f32_e32 v14, v15, v42
	v_and_b32_e32 v31, 0xffff0000, v31
	v_and_b32_e32 v35, 0xffff0000, v37
	v_fmac_f32_e32 v41, v22, v11
	v_fmac_f32_e32 v30, v27, v16
	v_sub_f32_e32 v16, v17, v32
	v_fmac_f32_e32 v42, v24, v14
	v_cndmask_b32_e64 v22, v34, 0, s[2:3]
	v_add_f32_e32 v24, v38, v38
	v_and_b32_e32 v33, 0xffff0000, v33
	v_fmac_f32_e32 v32, v23, v16
	v_cndmask_b32_e64 v23, v35, 0, s[2:3]
	v_sub_f32_e32 v22, v22, v31
	v_mul_f32_e32 v24, 0x3fb8aa3b, v24
	v_exp_f32_e32 v24, v24
	v_fmac_f32_e32 v31, v29, v22
	v_sub_f32_e32 v22, v23, v33
	v_add_f32_e32 v23, v30, v30
	global_load_dwordx4 v[6:9], v[4:5], off offset:3200
	global_load_dwordx4 v[10:13], v[2:3], off offset:3200
	v_mul_f32_e32 v23, 0x3fb8aa3b, v23
	v_exp_f32_e32 v23, v23
	global_load_dwordx4 v[14:17], v[122:123], off offset:16
	global_load_dwordx4 v[18:21], v[122:123], off
	v_fmac_f32_e32 v33, v25, v22
	v_add_f32_e32 v22, 1.0, v24
	v_add_f32_e32 v24, v39, v39
	v_mul_f32_e32 v24, 0x3fb8aa3b, v24
	v_exp_f32_e32 v24, v24
	v_rcp_f32_e32 v38, v22
	v_add_f32_e32 v22, 1.0, v23
	v_add_f32_e32 v23, v41, v41
	v_mul_f32_e32 v23, 0x3fb8aa3b, v23
	v_exp_f32_e32 v26, v23
	v_rcp_f32_e32 v39, v22
	v_add_f32_e32 v22, 1.0, v24
	v_rcp_f32_e32 v40, v22
	v_add_f32_e32 v22, v31, v31
	v_mul_f32_e32 v22, 0x3fb8aa3b, v22
	v_add_f32_e32 v30, 1.0, v26
	v_add_f32_e32 v26, v32, v32
	v_exp_f32_e32 v22, v22
	v_mul_f32_e32 v26, 0x3fb8aa3b, v26
	v_exp_f32_e32 v31, v26
	v_add_f32_e32 v26, v42, v42
	v_mul_f32_e32 v32, 0x3fb8aa3b, v26
	v_exp_f32_e32 v32, v32
	v_add_f32_e32 v27, 1.0, v22
	global_load_dwordx4 v[22:25], v[4:5], off offset:3264
	v_rcp_f32_e32 v41, v27
	global_load_dwordx4 v[26:29], v[2:3], off offset:3264
	v_rcp_f32_e32 v42, v30
	v_add_f32_e32 v30, 1.0, v31
	v_add_f32_e32 v31, v33, v33
	v_rcp_f32_e32 v43, v30
	v_add_f32_e32 v30, 1.0, v32
	v_mul_f32_e32 v31, 0x3fb8aa3b, v31
	v_exp_f32_e32 v45, v31
	v_rcp_f32_e32 v44, v30
	global_load_dwordx4 v[30:33], v[124:125], off offset:16
	global_load_dwordx4 v[34:37], v[124:125], off
	v_pk_fma_f32 v[38:39], v[38:39], 2.0, 1.0 op_sel_hi:[1,0,0] neg_lo:[1,0,0] neg_hi:[1,0,0]
	v_add_f32_e32 v45, 1.0, v45
	v_rcp_f32_e32 v45, v45
	v_pk_fma_f32 v[40:41], v[40:41], 2.0, 1.0 op_sel_hi:[1,0,0] neg_lo:[1,0,0] neg_hi:[1,0,0]
	v_pk_fma_f32 v[42:43], v[42:43], 2.0, 1.0 op_sel_hi:[1,0,0] neg_lo:[1,0,0] neg_hi:[1,0,0]
	v_cvt_pk_bf16_f32 v38, v38, v39
	v_pk_fma_f32 v[44:45], v[44:45], 2.0, 1.0 op_sel_hi:[1,0,0] neg_lo:[1,0,0] neg_hi:[1,0,0]
	v_cvt_pk_bf16_f32 v39, v40, v41
	v_cvt_pk_bf16_f32 v40, v42, v43
	v_cvt_pk_bf16_f32 v41, v44, v45
	ds_write_b128 v204, v[38:41] offset:53248
	s_waitcnt vmcnt(7)
	v_lshlrev_b32_e32 v46, 16, v6
	s_waitcnt vmcnt(6)
	v_lshlrev_b32_e32 v38, 16, v10
	v_lshlrev_b32_e32 v39, 16, v11
	v_and_b32_e32 v54, 0xffff0000, v11
	v_lshlrev_b32_e32 v11, 16, v12
	v_lshlrev_b32_e32 v50, 16, v8
	v_and_b32_e32 v40, 0xffff0000, v12
	v_cndmask_b32_e64 v12, v38, 0, s[2:3]
	v_cndmask_b32_e64 v11, v11, 0, s[2:3]
	v_and_b32_e32 v47, 0xffff0000, v6
	v_lshlrev_b32_e32 v48, 16, v7
	v_and_b32_e32 v49, 0xffff0000, v7
	v_and_b32_e32 v51, 0xffff0000, v8
	v_lshlrev_b32_e32 v52, 16, v9
	v_and_b32_e32 v53, 0xffff0000, v9
	v_and_b32_e32 v10, 0xffff0000, v10
	global_load_dwordx4 v[6:9], v[4:5], off offset:3328
	v_sub_f32_e32 v12, v12, v46
	v_sub_f32_e32 v11, v11, v50
	v_lshlrev_b32_e32 v41, 16, v13
	v_and_b32_e32 v55, 0xffff0000, v13
	s_waitcnt vmcnt(5)
	v_fmac_f32_e32 v46, v18, v12
	v_fmac_f32_e32 v50, v14, v11
	v_cndmask_b32_e64 v14, v10, 0, s[2:3]
	global_load_dwordx4 v[10:13], v[2:3], off offset:3328
	v_cndmask_b32_e64 v18, v40, 0, s[2:3]
	v_sub_f32_e32 v14, v14, v47
	v_fmac_f32_e32 v47, v19, v14
	v_sub_f32_e32 v14, v18, v51
	v_fmac_f32_e32 v51, v15, v14
	v_cndmask_b32_e64 v14, v39, 0, s[2:3]
	v_cndmask_b32_e64 v15, v41, 0, s[2:3]
	v_sub_f32_e32 v14, v14, v48
	v_fmac_f32_e32 v48, v20, v14
	v_sub_f32_e32 v14, v15, v52
	v_fmac_f32_e32 v52, v16, v14
	v_cndmask_b32_e64 v14, v54, 0, s[2:3]
	global_load_dwordx4 v[38:41], v[126:127], off offset:16
	global_load_dwordx4 v[42:45], v[126:127], off
	v_cndmask_b32_e64 v15, v55, 0, s[2:3]
	v_sub_f32_e32 v14, v14, v49
	v_fmac_f32_e32 v49, v21, v14
	v_sub_f32_e32 v14, v15, v53
	v_fmac_f32_e32 v53, v17, v14
	v_cvt_pk_bf16_f32 v14, v46, v47
	v_cvt_pk_bf16_f32 v15, v48, v49
	v_cvt_pk_bf16_f32 v16, v50, v51
	v_cvt_pk_bf16_f32 v17, v52, v53
	ds_write_b128 v204, v[14:17] offset:54272
	s_waitcnt vmcnt(7)
	v_lshlrev_b32_e32 v14, 16, v22
	v_and_b32_e32 v15, 0xffff0000, v22
	s_waitcnt vmcnt(6)
	v_lshlrev_b32_e32 v22, 16, v26
	v_lshlrev_b32_e32 v16, 16, v23
	v_and_b32_e32 v17, 0xffff0000, v23
	v_and_b32_e32 v23, 0xffff0000, v26
	v_lshlrev_b32_e32 v26, 16, v28
	v_cndmask_b32_e64 v22, v22, 0, s[2:3]
	v_lshlrev_b32_e32 v18, 16, v24
	v_cndmask_b32_e64 v26, v26, 0, s[2:3]
	v_sub_f32_e32 v22, v22, v14
	s_waitcnt vmcnt(4)
	v_fmac_f32_e32 v14, v34, v22
	v_sub_f32_e32 v22, v26, v18
	v_and_b32_e32 v19, 0xffff0000, v24
	v_lshlrev_b32_e32 v20, 16, v25
	v_and_b32_e32 v21, 0xffff0000, v25
	v_lshlrev_b32_e32 v24, 16, v27
	v_and_b32_e32 v25, 0xffff0000, v27
	v_and_b32_e32 v27, 0xffff0000, v28
	v_fmac_f32_e32 v18, v30, v22
	v_cndmask_b32_e64 v22, v23, 0, s[2:3]
	v_cndmask_b32_e64 v23, v27, 0, s[2:3]
	v_sub_f32_e32 v22, v22, v15
	v_fmac_f32_e32 v15, v35, v22
	v_sub_f32_e32 v22, v23, v19
	v_lshlrev_b32_e32 v28, 16, v29
	v_fmac_f32_e32 v19, v31, v22
	v_cndmask_b32_e64 v22, v24, 0, s[2:3]
	v_cndmask_b32_e64 v23, v28, 0, s[2:3]
	v_sub_f32_e32 v22, v22, v16
	v_fmac_f32_e32 v16, v36, v22
	v_sub_f32_e32 v22, v23, v20
	v_and_b32_e32 v29, 0xffff0000, v29
	v_fmac_f32_e32 v20, v32, v22
	v_cndmask_b32_e64 v22, v25, 0, s[2:3]
	v_cndmask_b32_e64 v23, v29, 0, s[2:3]
	v_sub_f32_e32 v22, v22, v17
	v_fmac_f32_e32 v17, v37, v22
	v_sub_f32_e32 v22, v23, v21
	v_fmac_f32_e32 v21, v33, v22
	v_cvt_pk_bf16_f32 v14, v14, v15
	v_cvt_pk_bf16_f32 v15, v16, v17
	v_cvt_pk_bf16_f32 v16, v18, v19
	v_cvt_pk_bf16_f32 v17, v20, v21
	ds_write_b128 v204, v[14:17] offset:55296
	global_load_dwordx4 v[14:17], v[4:5], off offset:3392
	s_waitcnt vmcnt(4)
	v_lshlrev_b32_e32 v22, 16, v6
	v_and_b32_e32 v23, 0xffff0000, v6
	v_lshlrev_b32_e32 v24, 16, v7
	v_and_b32_e32 v25, 0xffff0000, v7
	v_lshlrev_b32_e32 v26, 16, v8
	v_and_b32_e32 v27, 0xffff0000, v8
	v_lshlrev_b32_e32 v28, 16, v9
	v_and_b32_e32 v29, 0xffff0000, v9
	global_load_dwordx4 v[6:9], v[2:3], off offset:3392
	s_waitcnt vmcnt(4)
	v_lshlrev_b32_e32 v18, 16, v10
	v_and_b32_e32 v30, 0xffff0000, v10
	v_lshlrev_b32_e32 v31, 16, v11
	v_and_b32_e32 v32, 0xffff0000, v11
	v_lshlrev_b32_e32 v10, 16, v12
	v_cndmask_b32_e64 v11, v18, 0, s[2:3]
	v_and_b32_e32 v33, 0xffff0000, v12
	v_lshlrev_b32_e32 v34, 16, v13
	v_and_b32_e32 v35, 0xffff0000, v13
	v_cndmask_b32_e64 v36, v10, 0, s[2:3]
	v_sub_f32_e32 v37, v11, v22
	global_load_dwordx4 v[10:13], v[128:129], off offset:16
	global_load_dwordx4 v[18:21], v[128:129], off
	v_cndmask_b32_e64 v30, v30, 0, s[2:3]
	v_cndmask_b32_e64 v33, v33, 0, s[2:3]
	v_sub_f32_e32 v30, v30, v23
	s_waitcnt vmcnt(4)
	v_fmac_f32_e32 v23, v43, v30
	v_sub_f32_e32 v30, v33, v27
	v_fmac_f32_e32 v27, v39, v30
	v_cndmask_b32_e64 v30, v31, 0, s[2:3]
	v_cndmask_b32_e64 v31, v34, 0, s[2:3]
	v_sub_f32_e32 v30, v30, v24
	v_fmac_f32_e32 v24, v44, v30
	v_sub_f32_e32 v30, v31, v28
	v_fmac_f32_e32 v28, v40, v30
	v_cndmask_b32_e64 v30, v32, 0, s[2:3]
	v_cndmask_b32_e64 v31, v35, 0, s[2:3]
	v_sub_f32_e32 v30, v30, v25
	v_sub_f32_e32 v36, v36, v26
	v_fmac_f32_e32 v25, v45, v30
	v_sub_f32_e32 v30, v31, v29
	v_fmac_f32_e32 v22, v42, v37
	v_fmac_f32_e32 v26, v38, v36
	v_fmac_f32_e32 v29, v41, v30
	v_mul_f32_e32 v22, 0xbfb8aa3b, v22
	v_mul_f32_e32 v23, 0xbfb8aa3b, v23
	v_mul_f32_e32 v24, 0xbfb8aa3b, v24
	v_mul_f32_e32 v25, 0xbfb8aa3b, v25
	v_mul_f32_e32 v26, 0xbfb8aa3b, v26
	v_mul_f32_e32 v27, 0xbfb8aa3b, v27
	v_mul_f32_e32 v28, 0xbfb8aa3b, v28
	v_mul_f32_e32 v29, 0xbfb8aa3b, v29
	v_exp_f32_e32 v22, v22
	v_exp_f32_e32 v23, v23
	v_exp_f32_e32 v24, v24
	v_exp_f32_e32 v25, v25
	v_exp_f32_e32 v26, v26
	v_exp_f32_e32 v27, v27
	v_exp_f32_e32 v28, v28
	v_exp_f32_e32 v29, v29
	v_add_f32_e32 v22, 1.0, v22
	v_add_f32_e32 v23, 1.0, v23
	v_add_f32_e32 v24, 1.0, v24
	v_add_f32_e32 v25, 1.0, v25
	v_add_f32_e32 v26, 1.0, v26
	v_add_f32_e32 v27, 1.0, v27
	v_add_f32_e32 v28, 1.0, v28
	v_add_f32_e32 v29, 1.0, v29
	v_rcp_f32_e32 v22, v22
	v_rcp_f32_e32 v23, v23
	v_rcp_f32_e32 v24, v24
	v_rcp_f32_e32 v25, v25
	v_rcp_f32_e32 v26, v26
	v_rcp_f32_e32 v27, v27
	v_rcp_f32_e32 v28, v28
	v_rcp_f32_e32 v29, v29
	v_cvt_pk_bf16_f32 v22, v22, v23
	v_cvt_pk_bf16_f32 v23, v24, v25
	v_cvt_pk_bf16_f32 v24, v26, v27
	v_cvt_pk_bf16_f32 v25, v28, v29
	ds_write_b128 v204, v[22:25] offset:56320
	s_waitcnt vmcnt(3)
	v_lshlrev_b32_e32 v30, 16, v14
	v_and_b32_e32 v31, 0xffff0000, v14
	global_load_dwordx4 v[22:25], v[4:5], off offset:3456
	v_lshlrev_b32_e32 v32, 16, v15
	v_and_b32_e32 v33, 0xffff0000, v15
	v_lshlrev_b32_e32 v34, 16, v16
	v_and_b32_e32 v35, 0xffff0000, v16
	v_lshlrev_b32_e32 v36, 16, v17
	v_and_b32_e32 v37, 0xffff0000, v17
	global_load_dwordx4 v[14:17], v[2:3], off offset:3456
	s_waitcnt vmcnt(4)
	v_lshlrev_b32_e32 v26, 16, v6
	v_and_b32_e32 v38, 0xffff0000, v6
	v_lshlrev_b32_e32 v39, 16, v7
	v_and_b32_e32 v40, 0xffff0000, v7
	v_lshlrev_b32_e32 v6, 16, v8
	v_cndmask_b32_e64 v7, v26, 0, s[2:3]
	v_cndmask_b32_e64 v6, v6, 0, s[2:3]
	v_sub_f32_e32 v7, v7, v30
	v_and_b32_e32 v41, 0xffff0000, v8
	v_lshlrev_b32_e32 v42, 16, v9
	v_and_b32_e32 v43, 0xffff0000, v9
	s_waitcnt vmcnt(2)
	v_fmac_f32_e32 v30, v18, v7
	v_sub_f32_e32 v18, v6, v34
	global_load_dwordx4 v[6:9], v[130:131], off offset:16
	global_load_dwordx4 v[26:29], v[130:131], off
	v_fmac_f32_e32 v34, v10, v18
	v_cndmask_b32_e64 v10, v38, 0, s[2:3]
	v_cndmask_b32_e64 v18, v41, 0, s[2:3]
	v_sub_f32_e32 v10, v10, v31
	v_fmac_f32_e32 v31, v19, v10
	v_sub_f32_e32 v10, v18, v35
	v_fmac_f32_e32 v35, v11, v10
	v_cndmask_b32_e64 v10, v39, 0, s[2:3]
	v_cndmask_b32_e64 v11, v42, 0, s[2:3]
	v_sub_f32_e32 v10, v10, v32
	v_fmac_f32_e32 v32, v20, v10
	v_sub_f32_e32 v10, v11, v36
	v_fmac_f32_e32 v36, v12, v10
	v_cndmask_b32_e64 v10, v40, 0, s[2:3]
	v_cndmask_b32_e64 v11, v43, 0, s[2:3]
	v_sub_f32_e32 v10, v10, v33
	v_fmac_f32_e32 v33, v21, v10
	v_sub_f32_e32 v10, v11, v37
	v_mul_f32_e32 v11, 0xbfb8aa3b, v30
	v_mul_f32_e32 v12, 0xbfb8aa3b, v31
	v_exp_f32_e32 v11, v11
	v_exp_f32_e32 v12, v12
	v_fmac_f32_e32 v37, v13, v10
	v_mul_f32_e32 v13, 0xbfb8aa3b, v33
	v_add_f32_e32 v10, 1.0, v11
	v_add_f32_e32 v11, 1.0, v12
	v_mul_f32_e32 v12, 0xbfb8aa3b, v32
	v_mul_f32_e32 v18, 0xbfb8aa3b, v34
	v_mul_f32_e32 v19, 0xbfb8aa3b, v35
	v_mul_f32_e32 v20, 0xbfb8aa3b, v36
	v_mul_f32_e32 v21, 0xbfb8aa3b, v37
	v_exp_f32_e32 v12, v12
	v_exp_f32_e32 v13, v13
	v_exp_f32_e32 v18, v18
	v_exp_f32_e32 v19, v19
	v_exp_f32_e32 v20, v20
	v_exp_f32_e32 v21, v21
	v_add_f32_e32 v12, 1.0, v12
	v_add_f32_e32 v13, 1.0, v13
	v_add_f32_e32 v18, 1.0, v18
	v_add_f32_e32 v19, 1.0, v19
	v_add_f32_e32 v20, 1.0, v20
	v_add_f32_e32 v21, 1.0, v21
	v_rcp_f32_e32 v10, v10
	v_rcp_f32_e32 v11, v11
	v_rcp_f32_e32 v12, v12
	v_rcp_f32_e32 v13, v13
	v_rcp_f32_e32 v18, v18
	v_rcp_f32_e32 v19, v19
	v_rcp_f32_e32 v20, v20
	v_rcp_f32_e32 v21, v21
	v_cvt_pk_bf16_f32 v10, v10, v11
	v_cvt_pk_bf16_f32 v11, v12, v13
	v_cvt_pk_bf16_f32 v12, v18, v19
	v_cvt_pk_bf16_f32 v13, v20, v21
	ds_write_b128 v204, v[10:13] offset:57344
	global_load_dwordx4 v[10:13], v[4:5], off offset:3520
	s_waitcnt vmcnt(4)
	v_lshlrev_b32_e32 v30, 16, v22
	global_load_dwordx4 v[2:5], v[2:3], off offset:3520
	v_lshlrev_b32_e32 v32, 16, v24
	v_and_b32_e32 v22, 0xffff0000, v22
	v_and_b32_e32 v24, 0xffff0000, v24
	v_lshlrev_b32_e32 v31, 16, v23
	v_lshlrev_b32_e32 v33, 16, v25
	s_waitcnt vmcnt(4)
	v_lshlrev_b32_e32 v18, 16, v14
	v_and_b32_e32 v34, 0xffff0000, v14
	v_lshlrev_b32_e32 v35, 16, v15
	v_and_b32_e32 v36, 0xffff0000, v15
	v_lshlrev_b32_e32 v37, 16, v16
	v_and_b32_e32 v38, 0xffff0000, v16
	v_lshlrev_b32_e32 v39, 16, v17
	v_and_b32_e32 v40, 0xffff0000, v17
	v_cndmask_b32_e64 v41, v18, 0, s[2:3]
	global_load_dwordx4 v[14:17], v[132:133], off offset:16
	global_load_dwordx4 v[18:21], v[132:133], off
	v_cndmask_b32_e64 v37, v37, 0, s[2:3]
	v_sub_f32_e32 v41, v41, v30
	v_and_b32_e32 v23, 0xffff0000, v23
	v_and_b32_e32 v25, 0xffff0000, v25
	s_waitcnt vmcnt(4)
	v_fmac_f32_e32 v30, v26, v41
	v_sub_f32_e32 v26, v37, v32
	v_fmac_f32_e32 v32, v6, v26
	v_cndmask_b32_e64 v6, v34, 0, s[2:3]
	v_cndmask_b32_e64 v26, v38, 0, s[2:3]
	v_sub_f32_e32 v6, v6, v22
	v_fmac_f32_e32 v22, v27, v6
	v_sub_f32_e32 v6, v26, v24
	v_fmac_f32_e32 v24, v7, v6
	v_cndmask_b32_e64 v6, v35, 0, s[2:3]
	v_cndmask_b32_e64 v7, v39, 0, s[2:3]
	v_sub_f32_e32 v6, v6, v31
	v_fmac_f32_e32 v31, v28, v6
	v_sub_f32_e32 v6, v7, v33
	v_fmac_f32_e32 v33, v8, v6
	v_cndmask_b32_e64 v6, v36, 0, s[2:3]
	v_cndmask_b32_e64 v7, v40, 0, s[2:3]
	v_sub_f32_e32 v6, v6, v23
	v_fmac_f32_e32 v23, v29, v6
	v_sub_f32_e32 v6, v7, v25
	v_mul_f32_e32 v7, 0xbfb8aa3b, v30
	v_mul_f32_e32 v8, 0xbfb8aa3b, v22
	v_exp_f32_e32 v7, v7
	v_exp_f32_e32 v8, v8
	v_fmac_f32_e32 v25, v9, v6
	v_mul_f32_e32 v9, 0xbfb8aa3b, v23
	v_add_f32_e32 v6, 1.0, v7
	v_add_f32_e32 v7, 1.0, v8
	v_mul_f32_e32 v8, 0xbfb8aa3b, v31
	v_mul_f32_e32 v22, 0xbfb8aa3b, v32
	v_mul_f32_e32 v23, 0xbfb8aa3b, v24
	v_mul_f32_e32 v24, 0xbfb8aa3b, v33
	v_mul_f32_e32 v25, 0xbfb8aa3b, v25
	v_exp_f32_e32 v8, v8
	v_exp_f32_e32 v9, v9
	v_exp_f32_e32 v22, v22
	v_exp_f32_e32 v23, v23
	v_exp_f32_e32 v24, v24
	v_exp_f32_e32 v25, v25
	v_add_f32_e32 v8, 1.0, v8
	v_add_f32_e32 v9, 1.0, v9
	v_add_f32_e32 v22, 1.0, v22
	v_add_f32_e32 v23, 1.0, v23
	v_add_f32_e32 v24, 1.0, v24
	v_add_f32_e32 v25, 1.0, v25
	v_rcp_f32_e32 v6, v6
	v_rcp_f32_e32 v7, v7
	v_rcp_f32_e32 v8, v8
	v_rcp_f32_e32 v9, v9
	v_rcp_f32_e32 v22, v22
	v_rcp_f32_e32 v23, v23
	v_rcp_f32_e32 v24, v24
	v_rcp_f32_e32 v25, v25
	v_cvt_pk_bf16_f32 v6, v6, v7
	v_cvt_pk_bf16_f32 v7, v8, v9
	v_cvt_pk_bf16_f32 v8, v22, v23
	v_cvt_pk_bf16_f32 v9, v24, v25
	ds_write_b128 v204, v[6:9] offset:58368
	s_waitcnt vmcnt(3)
	v_and_b32_e32 v7, 0xffff0000, v10
	v_lshlrev_b32_e32 v8, 16, v11
	s_waitcnt vmcnt(2)
	v_lshlrev_b32_e32 v22, 16, v2
	v_and_b32_e32 v2, 0xffff0000, v2
	v_lshlrev_b32_e32 v24, 16, v4
	v_and_b32_e32 v4, 0xffff0000, v4
	v_cndmask_b32_e64 v2, v2, 0, s[2:3]
	v_and_b32_e32 v9, 0xffff0000, v11
	v_and_b32_e32 v11, 0xffff0000, v12
	v_cndmask_b32_e64 v4, v4, 0, s[2:3]
	v_sub_f32_e32 v2, v2, v7
	v_lshlrev_b32_e32 v23, 16, v3
	v_lshlrev_b32_e32 v25, 16, v5
	v_lshlrev_b32_e32 v6, 16, v10
	v_lshlrev_b32_e32 v10, 16, v12
	v_lshlrev_b32_e32 v12, 16, v13
	v_and_b32_e32 v3, 0xffff0000, v3
	s_waitcnt vmcnt(0)
	v_fmac_f32_e32 v7, v19, v2
	v_sub_f32_e32 v2, v4, v11
	v_fmac_f32_e32 v11, v15, v2
	v_cndmask_b32_e64 v2, v23, 0, s[2:3]
	v_cndmask_b32_e64 v4, v25, 0, s[2:3]
	v_sub_f32_e32 v2, v2, v8
	v_cndmask_b32_e64 v22, v22, 0, s[2:3]
	v_fmac_f32_e32 v8, v20, v2
	v_sub_f32_e32 v2, v4, v12
	v_and_b32_e32 v5, 0xffff0000, v5
	v_sub_f32_e32 v22, v22, v6
	v_fmac_f32_e32 v12, v16, v2
	v_cndmask_b32_e64 v2, v3, 0, s[2:3]
	v_and_b32_e32 v13, 0xffff0000, v13
	v_fmac_f32_e32 v6, v18, v22
	v_cndmask_b32_e64 v3, v5, 0, s[2:3]
	v_sub_f32_e32 v2, v2, v9
	v_fmac_f32_e32 v9, v21, v2
	v_sub_f32_e32 v2, v3, v13
	v_mul_f32_e32 v3, 0xbfb8aa3b, v6
	v_mul_f32_e32 v4, 0xbfb8aa3b, v7
	v_exp_f32_e32 v3, v3
	v_exp_f32_e32 v4, v4
	v_cndmask_b32_e64 v24, v24, 0, s[2:3]
	v_sub_f32_e32 v18, v24, v10
	v_fmac_f32_e32 v10, v14, v18
	v_fmac_f32_e32 v13, v17, v2
	v_add_f32_e32 v2, 1.0, v3
	v_add_f32_e32 v3, 1.0, v4
	v_mul_f32_e32 v4, 0xbfb8aa3b, v8
	v_mul_f32_e32 v5, 0xbfb8aa3b, v9
	v_mul_f32_e32 v6, 0xbfb8aa3b, v10
	v_mul_f32_e32 v7, 0xbfb8aa3b, v11
	v_mul_f32_e32 v8, 0xbfb8aa3b, v12
	v_mul_f32_e32 v9, 0xbfb8aa3b, v13
	v_exp_f32_e32 v4, v4
	v_exp_f32_e32 v5, v5
	v_exp_f32_e32 v6, v6
	v_exp_f32_e32 v7, v7
	v_exp_f32_e32 v8, v8
	v_exp_f32_e32 v9, v9
	v_add_f32_e32 v4, 1.0, v4
	v_add_f32_e32 v5, 1.0, v5
	v_add_f32_e32 v6, 1.0, v6
	v_add_f32_e32 v7, 1.0, v7
	v_add_f32_e32 v8, 1.0, v8
	v_add_f32_e32 v9, 1.0, v9
	v_rcp_f32_e32 v2, v2
	v_rcp_f32_e32 v3, v3
	v_rcp_f32_e32 v4, v4
	v_rcp_f32_e32 v5, v5
	v_rcp_f32_e32 v6, v6
	v_rcp_f32_e32 v7, v7
	v_rcp_f32_e32 v8, v8
	v_rcp_f32_e32 v9, v9
	v_cvt_pk_bf16_f32 v2, v2, v3
	v_cvt_pk_bf16_f32 v3, v4, v5
	v_cvt_pk_bf16_f32 v4, v6, v7
	v_cvt_pk_bf16_f32 v5, v8, v9
	ds_write_b128 v204, v[2:5] offset:59392
	s_branch .LBB0_1770
.Lprep_rest:
	s_waitcnt vmcnt(5)
	v_lshlrev_b32_e32 v211, 16, v12
	v_and_b32_e32 v212, 0xffff0000, v12
	v_lshlrev_b32_e32 v213, 16, v13
	v_and_b32_e32 v215, 0xffff0000, v13
	v_lshlrev_b32_e32 v214, 16, v14
	v_and_b32_e32 v216, 0xffff0000, v14
	v_lshlrev_b32_e32 v217, 16, v15
	v_and_b32_e32 v218, 0xffff0000, v15
	s_waitcnt vmcnt(3)
	v_lshlrev_b32_e32 v12, 16, v8
	v_and_b32_e32 v8, 0xffff0000, v8
	v_lshlrev_b32_e32 v13, 16, v9
	v_and_b32_e32 v9, 0xffff0000, v9
	v_lshlrev_b32_e32 v14, 16, v10
	v_and_b32_e32 v10, 0xffff0000, v10
	v_lshlrev_b32_e32 v15, 16, v11
	v_and_b32_e32 v11, 0xffff0000, v11
	v_cndmask_b32_e64 v32, v8, 0, s[2:3]
	v_cndmask_b32_e64 v44, v10, 0, s[2:3]
	v_cndmask_b32_e64 v108, v9, 0, s[2:3]
	v_cndmask_b32_e64 v109, v11, 0, s[2:3]
	v_lshlrev_b32_e32 v157, 16, v20
	v_and_b32_e32 v184, 0xffff0000, v20
	v_lshlrev_b32_e32 v185, 16, v21
	v_and_b32_e32 v207, 0xffff0000, v21
	v_lshlrev_b32_e32 v206, 16, v22
	v_and_b32_e32 v208, 0xffff0000, v22
	v_lshlrev_b32_e32 v209, 16, v23
	v_and_b32_e32 v210, 0xffff0000, v23
	v_lshlrev_b32_e32 v20, 16, v16
	v_and_b32_e32 v16, 0xffff0000, v16
	v_lshlrev_b32_e32 v21, 16, v17
	v_and_b32_e32 v17, 0xffff0000, v17
	v_lshlrev_b32_e32 v22, 16, v18
	v_and_b32_e32 v18, 0xffff0000, v18
	v_lshlrev_b32_e32 v23, 16, v19
	v_and_b32_e32 v19, 0xffff0000, v19
	v_cndmask_b32_e64 v20, v20, 0, s[2:3]
	v_cndmask_b32_e64 v22, v22, 0, s[2:3]
	v_cndmask_b32_e64 v16, v16, 0, s[2:3]
	v_cndmask_b32_e64 v18, v18, 0, s[2:3]
	v_cndmask_b32_e64 v21, v21, 0, s[2:3]
	v_cndmask_b32_e64 v23, v23, 0, s[2:3]
	v_cndmask_b32_e64 v17, v17, 0, s[2:3]
	v_cndmask_b32_e64 v19, v19, 0, s[2:3]
	v_cndmask_b32_e64 v12, v12, 0, s[2:3]
	v_cndmask_b32_e64 v14, v14, 0, s[2:3]
	v_cndmask_b32_e64 v45, v13, 0, s[2:3]
	v_cndmask_b32_e64 v46, v15, 0, s[2:3]
	v_sub_f32_e32 v227, v20, v157
	v_sub_f32_e32 v226, v22, v206
	v_sub_f32_e32 v225, v16, v184
	v_sub_f32_e32 v224, v18, v208
	v_sub_f32_e32 v223, v21, v185
	v_sub_f32_e32 v222, v23, v209
	v_sub_f32_e32 v221, v17, v207
	v_sub_f32_e32 v220, v19, v210
	v_sub_f32_e32 v219, v12, v211
	v_sub_f32_e32 v229, v14, v214
	v_sub_f32_e32 v228, v32, v212
	v_sub_f32_e32 v230, v44, v216
	v_sub_f32_e32 v232, v45, v213
	v_sub_f32_e32 v231, v46, v217
	v_sub_f32_e32 v234, v108, v215
	v_sub_f32_e32 v233, v109, v218
	v_lshl_add_u64 v[174:175], v[174:175], 0, s[12:13]
	v_lshl_add_u64 v[172:173], v[172:173], 0, s[14:15]
	v_lshl_add_u64 v[170:171], v[170:171], 0, s[14:15]
	v_lshl_add_u64 v[168:169], v[168:169], 0, s[14:15]
	v_lshl_add_u64 v[166:167], v[166:167], 0, s[12:13]
	s_waitcnt vmcnt(1)
	ds_write_b128 v198, v[24:27] offset:18432
	s_waitcnt vmcnt(0)
	ds_write_b128 v199, v[28:31] offset:18432
	s_waitcnt lgkmcnt(0)
	s_barrier
	ds_read_b128 v[8:11], v200 offset:9216
	ds_read_b128 v[12:15], v204 offset:54272
	ds_read_b128 v[16:19], v201 offset:18432
	ds_read_b128 v[32:35], v200
	ds_read_b128 v[36:39], v200 offset:9280
	ds_read_b128 v[28:31], v204 offset:55296
	ds_read_b128 v[20:23], v204 offset:56320
	s_waitcnt lgkmcnt(0)
	v_mfma_f32_16x16x32_bf16 v[76:79], v[16:19], v[20:23], 0
	v_mfma_f32_16x16x32_bf16 v[40:43], v[8:11], v[12:15], 0
	ds_read_b128 v[8:11], v204 offset:52224
	ds_read_b128 v[72:75], v201 offset:18496
	ds_read_b128 v[24:27], v204 offset:57344
	ds_read_b128 v[96:99], v200 offset:64
	ds_read_b128 v[16:19], v204 offset:53248
	ds_read_b128 v[80:83], v201 offset:18560
	v_mfma_f32_16x16x32_bf16 v[44:47], v[36:39], v[28:31], v[40:43]
	ds_read_b128 v[88:91], v141 offset:8192
	ds_read_b128 v[84:87], v141 offset:8208
	ds_read_b128 v[36:39], v204 offset:58368
	s_waitcnt lgkmcnt(2)
	v_fmac_f32_e32 v157, v227, v88
	v_mfma_f32_16x16x32_bf16 v[72:75], v[72:75], v[24:27], v[76:79]
	s_waitcnt lgkmcnt(1)
	v_fmac_f32_e32 v206, v226, v84
	v_fmac_f32_e32 v184, v225, v89
	v_fmac_f32_e32 v208, v224, v85
	v_mfma_f32_16x16x32_bf16 v[100:103], v[32:35], v[8:11], 0
	ds_read_b128 v[40:43], v141 offset:10240
	ds_read_b128 v[92:95], v141 offset:10256
	ds_read_b128 v[104:107], v201 offset:18624
	ds_read_b128 v[32:35], v204 offset:59392
	v_fmac_f32_e32 v185, v223, v90
	v_fmac_f32_e32 v209, v222, v86
	s_waitcnt lgkmcnt(4)
	v_mfma_f32_16x16x32_bf16 v[72:75], v[80:83], v[36:39], v[72:75]
	ds_read_b128 v[80:83], v141 offset:12288
	ds_read_b128 v[76:79], v141 offset:12304
	ds_read_b128 v[176:179], v141
	v_fmac_f32_e32 v207, v221, v91
	v_fmac_f32_e32 v210, v220, v87
	v_mfma_f32_16x16x32_bf16 v[180:183], v[96:99], v[16:19], v[100:103]
	ds_read_b128 v[96:99], v141 offset:16
	s_waitcnt lgkmcnt(3)
	v_fmac_f32_e32 v211, v219, v80
	s_waitcnt lgkmcnt(2)
	v_fmac_f32_e32 v214, v229, v76
	v_mfma_f32_16x16x32_bf16 v[72:75], v[104:107], v[32:35], v[72:75]
	v_fmac_f32_e32 v212, v228, v81
	s_waitcnt lgkmcnt(1)
	v_add_f32_e32 v112, v180, v176
	v_mul_f32_e64 v100, |v112|, s27
	v_exp_f32_e32 v100, v100
	v_max_f32_e64 v105, -v112, 0
	v_add_f32_e32 v112, v181, v177
	v_fmac_f32_e32 v216, v230, v77
	v_add_f32_e32 v100, 1.0, v100
	v_cmp_gt_f32_e32 vcc, s28, v100
	v_fmac_f32_e32 v213, v232, v82
	v_fmac_f32_e32 v217, v231, v78
	v_cndmask_b32_e64 v101, 0, 32, vcc
	v_ldexp_f32 v100, v100, v101
	v_log_f32_e32 v104, v100
	ds_read_b128 v[108:111], v141 offset:2048
	ds_read_b128 v[100:103], v141 offset:6144
	ds_read_b128 v[236:239], v201 offset:19520
	ds_read_b128 v[240:243], v201 offset:19584
	v_mul_f32_e32 v106, 0x3f317217, v104
	v_fma_f32 v106, v104, s29, -v106
	v_fmac_f32_e32 v106, 0x3377d1cf, v104
	v_fmac_f32_e32 v106, 0x3f317217, v104
	v_cmp_lt_f32_e64 s[0:1], |v104|, s30
	s_waitcnt lgkmcnt(3)
	v_add_f32_e32 v44, v44, v108
	v_mul_f32_e32 v44, 0xbfb8aa3b, v44
	v_cndmask_b32_e64 v104, v104, v106, s[0:1]
	v_cndmask_b32_e32 v106, 0, v205, vcc
	v_sub_f32_e32 v104, v104, v106
	v_add_f32_e32 v104, v105, v104
	v_mul_f32_e64 v105, |v112|, s27
	v_exp_f32_e32 v113, v105
	v_add_f32_e32 v45, v45, v109
	v_exp_f32_e32 v44, v44
	v_max_f32_e64 v112, -v112, 0
	v_add_f32_e32 v108, 1.0, v113
	v_cmp_gt_f32_e32 vcc, s28, v108
	v_mul_f32_e32 v45, 0xbfb8aa3b, v45
	v_exp_f32_e32 v45, v45
	v_cndmask_b32_e64 v113, 0, 32, vcc
	v_ldexp_f32 v108, v108, v113
	v_log_f32_e32 v108, v108
	v_add_f32_e32 v44, 1.0, v44
	v_sub_f32_e32 v104, -0.5, v104
	v_mul_f32_e32 v104, 0x3fb8aa3b, v104
	v_mul_f32_e32 v113, 0x3f317217, v108
	v_fma_f32 v113, v108, s29, -v113
	v_fmac_f32_e32 v113, 0x3377d1cf, v108
	v_fmac_f32_e32 v113, 0x3f317217, v108
	v_cmp_lt_f32_e64 s[0:1], |v108|, s30
	v_exp_f32_e32 v104, v104
	v_fmac_f32_e32 v215, v234, v83
	v_cndmask_b32_e64 v108, v108, v113, s[0:1]
	v_cndmask_b32_e32 v113, 0, v205, vcc
	v_sub_f32_e32 v108, v108, v113
	v_add_f32_e32 v108, v112, v108
	v_sub_f32_e32 v108, -0.5, v108
	v_mul_f32_e32 v108, 0x3fb8aa3b, v108
	v_exp_f32_e32 v112, v108
	v_rcp_f32_e32 v108, v44
	v_add_f32_e32 v44, 1.0, v45
	v_rcp_f32_e32 v109, v44
	v_lshlrev_b32_e32 v44, 16, v68
	v_and_b32_e32 v45, 0xffff0000, v68
	v_lshlrev_b32_e32 v68, 16, v64
	v_and_b32_e32 v64, 0xffff0000, v64
	v_cndmask_b32_e64 v113, v64, 0, s[2:3]
	v_add_f32_e32 v64, v182, v178
	v_xor_b32_e32 v248, 0x80000000, v112
	v_cndmask_b32_e64 v112, v68, 0, s[2:3]
	v_mul_f32_e64 v68, |v64|, s27
	v_exp_f32_e32 v68, v68
	v_pk_add_f32 v[112:113], v[112:113], v[44:45] neg_lo:[0,1] neg_hi:[0,1]
	v_xor_b32_e32 v235, 0x80000000, v104
	v_pk_fma_f32 v[176:177], v[112:113], v[40:41], v[44:45]
	v_add_f32_e32 v44, 1.0, v68
	v_cmp_gt_f32_e32 vcc, s28, v44
	v_pk_add_f32 v[40:41], v[108:109], -1.0 op_sel_hi:[1,0]
	ds_read_b128 v[104:107], v141 offset:2064
	ds_read_b128 v[112:115], v141 offset:6160
	v_cndmask_b32_e64 v45, 0, 32, vcc
	v_ldexp_f32 v44, v44, v45
	v_log_f32_e32 v44, v44
	s_waitcnt lgkmcnt(4)
	v_pk_fma_f32 v[40:41], v[100:101], v[40:41], 1.0 op_sel_hi:[1,1,0]
	v_add_f32_e32 v45, v46, v110
	v_pk_mul_f32 v[186:187], v[176:177], v[40:41]
	v_mul_f32_e32 v41, 0x3f317217, v44
	v_fma_f32 v41, v44, s29, -v41
	v_fmac_f32_e32 v41, 0x3377d1cf, v44
	v_fmac_f32_e32 v41, 0x3f317217, v44
	v_cmp_lt_f32_e64 s[0:1], |v44|, s30
	v_max_f32_e64 v40, -v64, 0
	v_mul_f32_e32 v45, 0xbfb8aa3b, v45
	v_cndmask_b32_e64 v41, v44, v41, s[0:1]
	v_cndmask_b32_e32 v44, 0, v205, vcc
	v_sub_f32_e32 v41, v41, v44
	v_add_f32_e32 v40, v40, v41
	v_add_f32_e32 v41, v183, v179
	v_mul_f32_e64 v44, |v41|, s27
	v_exp_f32_e32 v44, v44
	v_sub_f32_e32 v40, -0.5, v40
	v_mul_f32_e32 v40, 0x3fb8aa3b, v40
	v_exp_f32_e32 v40, v40
	v_add_f32_e32 v44, 1.0, v44
	v_cmp_gt_f32_e32 vcc, s28, v44
	v_exp_f32_e32 v45, v45
	v_xor_b32_e32 v100, 0x80000000, v40
	v_cndmask_b32_e64 v46, 0, 32, vcc
	v_ldexp_f32 v44, v44, v46
	v_log_f32_e32 v44, v44
	v_add_f32_e32 v40, 1.0, v45
	v_max_f32_e64 v41, -v41, 0
	ds_read_b128 v[178:181], v200 offset:9856
	v_mul_f32_e32 v45, 0x3f317217, v44
	v_fma_f32 v45, v44, s29, -v45
	v_fmac_f32_e32 v45, 0x3377d1cf, v44
	v_fmac_f32_e32 v45, 0x3f317217, v44
	v_cmp_lt_f32_e64 s[0:1], |v44|, s30
	v_rcp_f32_e32 v110, v40
	v_cvt_pk_bf16_f32 v68, v235, v248
	v_cndmask_b32_e64 v44, v44, v45, s[0:1]
	v_cndmask_b32_e32 v45, 0, v205, vcc
	v_sub_f32_e32 v44, v44, v45
	v_add_f32_e32 v41, v41, v44
	v_add_f32_e32 v44, v47, v111
	v_mul_f32_e32 v64, 0xbfb8aa3b, v44
	ds_read_b128 v[44:47], v200 offset:9792
	s_waitcnt lgkmcnt(0)
	v_mfma_f32_16x16x32_bf16 v[44:47], v[44:47], v[12:15], 0
	v_exp_f32_e32 v64, v64
	v_sub_f32_e32 v41, -0.5, v41
	v_mul_f32_e32 v41, 0x3fb8aa3b, v41
	v_mfma_f32_16x16x32_bf16 v[244:247], v[178:181], v[28:31], v[44:47]
	v_add_f32_e32 v40, 1.0, v64
	v_lshlrev_b32_e32 v64, 16, v65
	v_exp_f32_e32 v41, v41
	s_nop 0
	v_and_b32_e32 v44, 0xffff0000, v65
	v_cndmask_b32_e64 v65, v44, 0, s[2:3]
	ds_read_b128 v[44:47], v200 offset:576
	v_rcp_f32_e32 v111, v40
	v_mfma_f32_16x16x32_bf16 v[178:181], v[236:239], v[20:23], 0
	ds_read_b128 v[236:239], v200 offset:640
	v_xor_b32_e32 v101, 0x80000000, v41
	v_lshlrev_b32_e32 v40, 16, v69
	v_and_b32_e32 v41, 0xffff0000, v69
	v_cndmask_b32_e64 v64, v64, 0, s[2:3]
	v_pk_add_f32 v[64:65], v[64:65], v[40:41] neg_lo:[0,1] neg_hi:[0,1]
	v_mfma_f32_16x16x32_bf16 v[180:183], v[240:243], v[24:27], v[178:181]
	v_cvt_pk_bf16_f32 v69, v100, v101
	v_fmac_f32_e32 v218, v233, v79
	v_lshlrev_b32_e32 v219, 16, v55
	v_pk_fma_f32 v[178:179], v[64:65], v[42:43], v[40:41]
	v_pk_add_f32 v[40:41], v[110:111], -1.0 op_sel_hi:[1,0]
	v_and_b32_e32 v220, 0xffff0000, v55
	v_pk_fma_f32 v[64:65], v[102:103], v[40:41], 1.0 op_sel_hi:[1,1,0]
	s_waitcnt lgkmcnt(1)
	v_mfma_f32_16x16x32_bf16 v[40:43], v[44:47], v[8:11], 0
	ds_read_b128 v[44:47], v201 offset:19648
	v_pk_mul_f32 v[64:65], v[178:179], v[64:65]
	v_lshlrev_b32_e32 v84, 16, v48
	s_waitcnt lgkmcnt(1)
	v_mfma_f32_16x16x32_bf16 v[236:239], v[236:239], v[16:19], v[40:43]
	v_and_b32_e32 v88, 0xffff0000, v48
	v_lshlrev_b32_e32 v48, 16, v50
	v_and_b32_e32 v89, 0xffff0000, v50
	v_cndmask_b32_e64 v85, v48, 0, s[2:3]
	v_cndmask_b32_e64 v84, v84, 0, s[2:3]
	s_nop 2
	v_add_f32_e32 v96, v236, v96
	v_mul_f32_e64 v40, |v96|, s27
	v_exp_f32_e32 v102, v40
	ds_read_b128 v[40:43], v201 offset:19712
	s_waitcnt lgkmcnt(1)
	v_mfma_f32_16x16x32_bf16 v[44:47], v[44:47], v[36:39], v[180:183]
	v_add_f32_e32 v97, v237, v97
	v_add_f32_e32 v100, 1.0, v102
	v_cmp_gt_f32_e32 vcc, s28, v100
	v_lshl_add_u64 v[180:181], v[162:163], 0, s[16:17]
	v_cndmask_b32_e64 v88, v88, 0, s[2:3]
	v_cndmask_b32_e64 v101, 0, 32, vcc
	v_ldexp_f32 v100, v100, v101
	v_log_f32_e32 v182, v100
	s_waitcnt lgkmcnt(0)
	v_mfma_f32_16x16x32_bf16 v[100:103], v[40:43], v[32:35], v[44:47]
	v_cndmask_b32_e32 v42, 0, v205, vcc
	v_max_f32_e64 v40, -v96, 0
	v_mul_f32_e32 v41, 0x3f317217, v182
	v_fma_f32 v41, v182, s29, -v41
	v_fmac_f32_e32 v41, 0x3377d1cf, v182
	v_fmac_f32_e32 v41, 0x3f317217, v182
	v_cmp_lt_f32_e64 s[0:1], |v182|, s30
	v_cndmask_b32_e64 v89, v89, 0, s[2:3]
	s_nop 0
	v_cndmask_b32_e64 v41, v182, v41, s[0:1]
	v_sub_f32_e32 v41, v41, v42
	v_add_f32_e32 v40, v40, v41
	v_sub_f32_e32 v40, -0.5, v40
	v_mul_f32_e32 v40, 0x3fb8aa3b, v40
	v_exp_f32_e32 v96, v40
	v_mul_f32_e64 v40, |v97|, s27
	v_exp_f32_e32 v182, v40
	v_max_f32_e64 v97, -v97, 0
	v_xor_b32_e32 v235, 0x80000000, v96
	v_add_f32_e32 v96, v244, v104
	v_add_f32_e32 v104, 1.0, v182
	v_cmp_gt_f32_e32 vcc, s28, v104
	v_mul_f32_e32 v96, 0xbfb8aa3b, v96
	v_exp_f32_e32 v96, v96
	v_cndmask_b32_e64 v182, 0, 32, vcc
	v_ldexp_f32 v104, v104, v182
	v_log_f32_e32 v104, v104
	v_add_f32_e32 v96, 1.0, v96
	ds_read_b128 v[40:43], v141 offset:4096
	ds_read_b128 v[44:47], v141 offset:4112
	v_mul_f32_e32 v182, 0x3f317217, v104
	v_fma_f32 v182, v104, s29, -v182
	v_fmac_f32_e32 v182, 0x3377d1cf, v104
	v_fmac_f32_e32 v182, 0x3f317217, v104
	v_cmp_lt_f32_e64 s[0:1], |v104|, s30
	s_nop 1
	v_cndmask_b32_e64 v104, v104, v182, s[0:1]
	v_cndmask_b32_e32 v182, 0, v205, vcc
	v_sub_f32_e32 v104, v104, v182
	v_add_f32_e32 v97, v97, v104
	v_add_f32_e32 v104, v245, v105
	v_sub_f32_e32 v97, -0.5, v97
	v_mul_f32_e32 v104, 0xbfb8aa3b, v104
	v_mul_f32_e32 v97, 0x3fb8aa3b, v97
	v_exp_f32_e32 v105, v104
	v_exp_f32_e32 v97, v97
	v_rcp_f32_e32 v104, v96
	v_add_f32_e32 v96, 1.0, v105
	v_xor_b32_e32 v236, 0x80000000, v97
	v_rcp_f32_e32 v105, v96
	v_lshlrev_b32_e32 v96, 16, v70
	v_and_b32_e32 v97, 0xffff0000, v70
	v_lshlrev_b32_e32 v70, 16, v66
	v_and_b32_e32 v66, 0xffff0000, v66
	v_cndmask_b32_e64 v183, v66, 0, s[2:3]
	v_add_f32_e32 v66, v238, v98
	v_mul_f32_e64 v98, |v66|, s27
	v_exp_f32_e32 v98, v98
	v_cndmask_b32_e64 v182, v70, 0, s[2:3]
	v_pk_add_f32 v[182:183], v[182:183], v[96:97] neg_lo:[0,1] neg_hi:[0,1]
	v_max_f32_e64 v66, -v66, 0
	v_add_f32_e32 v70, 1.0, v98
	v_cmp_gt_f32_e32 vcc, s28, v70
	v_pk_fma_f32 v[182:183], v[182:183], v[92:93], v[96:97]
	s_nop 0
	v_cndmask_b32_e64 v92, 0, 32, vcc
	v_ldexp_f32 v70, v70, v92
	v_log_f32_e32 v70, v70
	v_pk_add_f32 v[92:93], v[104:105], -1.0 op_sel_hi:[1,0]
	v_mul_f32_e32 v96, 0x3f317217, v70
	v_fma_f32 v96, v70, s29, -v96
	v_fmac_f32_e32 v96, 0x3377d1cf, v70
	v_fmac_f32_e32 v96, 0x3f317217, v70
	v_cmp_lt_f32_e64 s[0:1], |v70|, s30
	v_pk_fma_f32 v[92:93], v[112:113], v[92:93], 1.0 op_sel_hi:[1,1,0]
	s_nop 0
	v_cndmask_b32_e64 v70, v70, v96, s[0:1]
	v_cndmask_b32_e32 v96, 0, v205, vcc
	v_sub_f32_e32 v70, v70, v96
	v_add_f32_e32 v66, v66, v70
	v_add_f32_e32 v70, v239, v99
	v_mul_f32_e64 v96, |v70|, s27
	v_exp_f32_e32 v96, v96
	v_sub_f32_e32 v66, -0.5, v66
	v_mul_f32_e32 v66, 0x3fb8aa3b, v66
	v_exp_f32_e32 v66, v66
	v_add_f32_e32 v96, 1.0, v96
	v_cmp_gt_f32_e32 vcc, s28, v96
	v_max_f32_e64 v70, -v70, 0
	v_xor_b32_e32 v97, 0x80000000, v66
	v_cndmask_b32_e64 v98, 0, 32, vcc
	v_ldexp_f32 v96, v96, v98
	v_log_f32_e32 v96, v96
	v_add_f32_e32 v66, v246, v106
	v_mul_f32_e32 v66, 0xbfb8aa3b, v66
	v_exp_f32_e32 v66, v66
	v_mul_f32_e32 v98, 0x3f317217, v96
	v_fma_f32 v98, v96, s29, -v98
	v_fmac_f32_e32 v98, 0x3377d1cf, v96
	v_fmac_f32_e32 v98, 0x3f317217, v96
	v_cmp_lt_f32_e64 s[0:1], |v96|, s30
	v_add_f32_e32 v66, 1.0, v66
	v_rcp_f32_e32 v106, v66
	v_cndmask_b32_e64 v96, v96, v98, s[0:1]
	v_cndmask_b32_e32 v98, 0, v205, vcc
	v_sub_f32_e32 v96, v96, v98
	v_add_f32_e32 v70, v70, v96
	v_add_f32_e32 v96, v247, v107
	v_mul_f32_e32 v96, 0xbfb8aa3b, v96
	v_exp_f32_e32 v96, v96
	v_sub_f32_e32 v70, -0.5, v70
	v_mul_f32_e32 v70, 0x3fb8aa3b, v70
	v_exp_f32_e32 v70, v70
	v_add_f32_e32 v66, 1.0, v96
	v_rcp_f32_e32 v107, v66
	v_lshlrev_b32_e32 v66, 16, v67
	v_and_b32_e32 v67, 0xffff0000, v67
	v_xor_b32_e32 v98, 0x80000000, v70
	v_lshlrev_b32_e32 v70, 16, v71
	v_and_b32_e32 v71, 0xffff0000, v71
	v_cndmask_b32_e64 v67, v67, 0, s[2:3]
	v_cndmask_b32_e64 v66, v66, 0, s[2:3]
	v_pk_add_f32 v[66:67], v[66:67], v[70:71] neg_lo:[0,1] neg_hi:[0,1]
	v_pk_mul_f32 v[92:93], v[182:183], v[92:93]
	v_pk_fma_f32 v[112:113], v[66:67], v[94:95], v[70:71]
	v_pk_add_f32 v[66:67], v[106:107], -1.0 op_sel_hi:[1,0]
	v_cvt_pk_bf16_f32 v70, v235, v236
	v_pk_fma_f32 v[66:67], v[114:115], v[66:67], 1.0 op_sel_hi:[1,1,0]
	v_add_co_u32_e32 v114, vcc, s31, v180
	v_cvt_pk_bf16_f32 v71, v97, v98
	s_nop 0
	v_addc_co_u32_e32 v115, vcc, 0, v181, vcc
	v_pk_mul_f32 v[94:95], v[112:113], v[66:67]
	global_store_dwordx4 v[114:115], v[68:71], off
	v_cvt_pk_bf16_f32 v66, v157, v184
	v_cvt_pk_bf16_f32 v67, v185, v207
	v_cvt_pk_bf16_f32 v68, v206, v208
	v_cvt_pk_bf16_f32 v69, v209, v210
	v_add_co_u32_e32 v184, vcc, s33, v180
	global_store_dwordx4 v[180:181], v[66:69], off
	s_nop 0
	v_addc_co_u32_e32 v185, vcc, 0, v181, vcc
	v_cvt_pk_bf16_f32 v66, v211, v212
	v_cvt_pk_bf16_f32 v67, v213, v215
	v_cvt_pk_bf16_f32 v68, v214, v216
	v_cvt_pk_bf16_f32 v69, v217, v218
	global_store_dwordx4 v[184:185], v[66:69], off
	v_lshlrev_b32_e32 v157, 16, v60
	v_and_b32_e32 v206, 0xffff0000, v60
	v_cvt_pk_bf16_f32 v66, v186, v187
	v_add_co_u32_e32 v186, vcc, s34, v180
	v_cvt_pk_bf16_f32 v67, v64, v65
	v_cvt_pk_bf16_f32 v68, v92, v93
	v_cvt_pk_bf16_f32 v69, v94, v95
	v_addc_co_u32_e32 v187, vcc, 0, v181, vcc
	global_store_dwordx4 v[186:187], v[66:69], off
	v_lshlrev_b32_e32 v60, 16, v56
	v_and_b32_e32 v56, 0xffff0000, v56
	v_cvt_pk_bf16_f32 v66, v100, v101
	v_lshl_add_u64 v[100:101], v[160:161], 0, s[16:17]
	v_cvt_pk_bf16_f32 v67, v102, v103
	v_add_co_u32_e32 v102, vcc, s35, v100
	v_lshlrev_b32_e32 v207, 16, v61
	v_and_b32_e32 v209, 0xffff0000, v61
	v_lshlrev_b32_e32 v208, 16, v62
	v_and_b32_e32 v210, 0xffff0000, v62
	v_lshlrev_b32_e32 v61, 16, v57
	v_lshlrev_b32_e32 v62, 16, v58
	v_and_b32_e32 v58, 0xffff0000, v58
	v_cndmask_b32_e64 v56, v56, 0, s[2:3]
	v_cvt_pk_bf16_f32 v64, v72, v73
	v_cvt_pk_bf16_f32 v65, v74, v75
	v_addc_co_u32_e32 v103, vcc, 0, v101, vcc
	v_lshlrev_b32_e32 v211, 16, v63
	v_and_b32_e32 v212, 0xffff0000, v63
	v_and_b32_e32 v57, 0xffff0000, v57
	v_lshlrev_b32_e32 v63, 16, v59
	v_and_b32_e32 v59, 0xffff0000, v59
	v_cndmask_b32_e64 v58, v58, 0, s[2:3]
	v_sub_f32_e32 v226, v56, v206
	v_cndmask_b32_e64 v56, v61, 0, s[2:3]
	global_store_dwordx4 v[102:103], v[64:67], off
	v_cndmask_b32_e64 v60, v60, 0, s[2:3]
	v_cndmask_b32_e64 v62, v62, 0, s[2:3]
	v_sub_f32_e32 v222, v58, v210
	v_cndmask_b32_e64 v58, v63, 0, s[2:3]
	v_sub_f32_e32 v227, v56, v207
	v_cndmask_b32_e64 v56, v57, 0, s[2:3]
	v_cndmask_b32_e64 v57, v59, 0, s[2:3]
	ds_read_b128 v[68:71], v141 offset:8320
	ds_read_b128 v[64:67], v141 offset:8336
	v_sub_f32_e32 v225, v60, v157
	v_sub_f32_e32 v221, v62, v208
	v_sub_f32_e32 v223, v58, v211
	v_sub_f32_e32 v228, v56, v209
	v_sub_f32_e32 v224, v57, v212
	ds_read_b128 v[76:79], v141 offset:10368
	ds_read_b128 v[72:75], v141 offset:10384
	ds_read_b128 v[60:63], v141 offset:12416
	ds_read_b128 v[56:59], v141 offset:12432
	v_lshlrev_b32_e32 v213, 16, v52
	v_and_b32_e32 v214, 0xffff0000, v52
	v_lshlrev_b32_e32 v215, 16, v53
	v_and_b32_e32 v217, 0xffff0000, v53
	v_lshlrev_b32_e32 v216, 16, v54
	v_and_b32_e32 v218, 0xffff0000, v54
	ds_read_b128 v[52:55], v200 offset:13824
	ds_read_b128 v[80:83], v200 offset:13888
	v_lshlrev_b32_e32 v92, 16, v49
	v_and_b32_e32 v96, 0xffff0000, v49
	v_lshlrev_b32_e32 v97, 16, v51
	v_and_b32_e32 v98, 0xffff0000, v51
	ds_read_b128 v[48:51], v201 offset:27136
	v_sub_f32_e32 v230, v84, v213
	v_sub_f32_e32 v229, v85, v216
	ds_read_b128 v[84:87], v201 offset:27200
	v_sub_f32_e32 v232, v88, v214
	v_sub_f32_e32 v231, v89, v218
	ds_read_b128 v[88:91], v200 offset:4608
	s_waitcnt lgkmcnt(4)
	v_mfma_f32_16x16x32_bf16 v[52:55], v[52:55], v[12:15], 0
	v_cndmask_b32_e64 v99, v92, 0, s[2:3]
	v_sub_f32_e32 v234, v99, v215
	v_fmac_f32_e32 v157, v225, v68
	s_waitcnt lgkmcnt(3)
	v_mfma_f32_16x16x32_bf16 v[80:83], v[80:83], v[28:31], v[52:55]
	v_fmac_f32_e32 v208, v221, v64
	v_fmac_f32_e32 v206, v226, v69
	v_fmac_f32_e32 v210, v222, v65
	ds_read_b128 v[52:55], v201 offset:27264
	s_waitcnt lgkmcnt(3)
	v_mfma_f32_16x16x32_bf16 v[48:51], v[48:51], v[20:23], 0
	v_fmac_f32_e32 v207, v227, v70
	v_fmac_f32_e32 v211, v223, v66
	v_fmac_f32_e32 v209, v228, v71
	s_waitcnt lgkmcnt(2)
	v_mfma_f32_16x16x32_bf16 v[48:51], v[84:87], v[24:27], v[48:51]
	ds_read_b128 v[84:87], v200 offset:4672
	ds_read_b128 v[92:95], v201 offset:27328
	ds_read_b128 v[236:239], v141 offset:128
	v_fmac_f32_e32 v212, v224, v67
	s_waitcnt lgkmcnt(3)
	v_mfma_f32_16x16x32_bf16 v[48:51], v[52:55], v[36:39], v[48:51]
	v_cndmask_b32_e64 v52, v97, 0, s[2:3]
	v_sub_f32_e32 v233, v52, v219
	v_fmac_f32_e32 v213, v230, v60
	v_mfma_f32_16x16x32_bf16 v[52:55], v[88:91], v[8:11], 0
	v_cndmask_b32_e64 v88, v96, 0, s[2:3]
	v_cndmask_b32_e64 v89, v98, 0, s[2:3]
	v_sub_f32_e32 v235, v89, v220
	s_waitcnt lgkmcnt(2)
	v_mfma_f32_16x16x32_bf16 v[240:243], v[84:87], v[16:19], v[52:55]
	v_fmac_f32_e32 v216, v229, v56
	v_fmac_f32_e32 v214, v232, v61
	v_fmac_f32_e32 v218, v231, v57
	ds_read_b128 v[52:55], v141 offset:144
	s_waitcnt lgkmcnt(2)
	v_mfma_f32_16x16x32_bf16 v[48:51], v[92:95], v[32:35], v[48:51]
	s_waitcnt lgkmcnt(1)
	s_nop 0
	v_add_f32_e32 v90, v240, v236
	v_mul_f32_e64 v84, |v90|, s27
	v_exp_f32_e32 v84, v84
	v_sub_f32_e32 v236, v88, v217
	v_max_f32_e64 v89, -v90, 0
	v_add_f32_e32 v96, v241, v237
	v_add_f32_e32 v84, 1.0, v84
	v_cmp_gt_f32_e32 vcc, s28, v84
	v_fmac_f32_e32 v215, v234, v62
	v_fmac_f32_e32 v219, v233, v58
	v_cndmask_b32_e64 v85, 0, 32, vcc
	v_ldexp_f32 v84, v84, v85
	v_log_f32_e32 v88, v84
	ds_read_b128 v[92:95], v141 offset:2176
	ds_read_b128 v[84:87], v141 offset:6272
	ds_read_b128 v[246:249], v201 offset:28224
	v_fmac_f32_e32 v217, v236, v63
	v_mul_f32_e32 v90, 0x3f317217, v88
	v_fma_f32 v90, v88, s29, -v90
	v_fmac_f32_e32 v90, 0x3377d1cf, v88
	v_fmac_f32_e32 v90, 0x3f317217, v88
	v_cmp_lt_f32_e64 s[0:1], |v88|, s30
	s_waitcnt lgkmcnt(2)
	v_add_f32_e32 v80, v80, v92
	v_add_f32_e32 v81, v81, v93
	v_cndmask_b32_e64 v88, v88, v90, s[0:1]
	v_cndmask_b32_e32 v90, 0, v205, vcc
	v_sub_f32_e32 v88, v88, v90
	v_add_f32_e32 v88, v89, v88
	v_mul_f32_e64 v89, |v96|, s27
	v_exp_f32_e32 v97, v89
	v_max_f32_e64 v96, -v96, 0
	v_and_b32_e32 v93, 0xffff0000, v4
	v_mul_f32_e32 v80, 0xbfb8aa3b, v80
	v_add_f32_e32 v92, 1.0, v97
	v_cmp_gt_f32_e32 vcc, s28, v92
	v_mul_f32_e32 v81, 0xbfb8aa3b, v81
	v_exp_f32_e32 v80, v80
	v_cndmask_b32_e64 v97, 0, 32, vcc
	v_ldexp_f32 v92, v92, v97
	v_log_f32_e32 v92, v92
	v_exp_f32_e32 v81, v81
	v_add_f32_e32 v80, 1.0, v80
	v_rcp_f32_e32 v80, v80
	v_mul_f32_e32 v97, 0x3f317217, v92
	v_fma_f32 v97, v92, s29, -v97
	v_fmac_f32_e32 v97, 0x3377d1cf, v92
	v_fmac_f32_e32 v97, 0x3f317217, v92
	v_cmp_lt_f32_e64 s[0:1], |v92|, s30
	v_add_f32_e32 v81, 1.0, v81
	v_rcp_f32_e32 v81, v81
	v_cndmask_b32_e64 v92, v92, v97, s[0:1]
	v_cndmask_b32_e32 v97, 0, v205, vcc
	v_sub_f32_e32 v92, v92, v97
	v_add_f32_e32 v92, v96, v92
	v_sub_f32_e32 v92, -0.5, v92
	v_mul_f32_e32 v92, 0x3fb8aa3b, v92
	v_exp_f32_e32 v92, v92
	v_sub_f32_e32 v88, -0.5, v88
	v_mul_f32_e32 v88, 0x3fb8aa3b, v88
	v_exp_f32_e32 v88, v88
	v_xor_b32_e32 v250, 0x80000000, v92
	v_lshlrev_b32_e32 v92, 16, v4
	v_lshlrev_b32_e32 v4, 16, v0
	v_and_b32_e32 v0, 0xffff0000, v0
	v_cndmask_b32_e64 v97, v0, 0, s[2:3]
	v_add_f32_e32 v0, v242, v238
	v_cndmask_b32_e64 v96, v4, 0, s[2:3]
	v_mul_f32_e64 v4, |v0|, s27
	v_exp_f32_e32 v4, v4
	v_pk_add_f32 v[96:97], v[96:97], v[92:93] neg_lo:[0,1] neg_hi:[0,1]
	v_max_f32_e64 v0, -v0, 0
	v_pk_fma_f32 v[92:93], v[96:97], v[76:77], v[92:93]
	v_add_f32_e32 v4, 1.0, v4
	v_cmp_gt_f32_e32 vcc, s28, v4
	v_pk_add_f32 v[76:77], v[80:81], -1.0 op_sel_hi:[1,0]
	v_xor_b32_e32 v237, 0x80000000, v88
	v_cndmask_b32_e64 v96, 0, 32, vcc
	v_ldexp_f32 v4, v4, v96
	v_log_f32_e32 v4, v4
	s_waitcnt lgkmcnt(1)
	v_pk_fma_f32 v[76:77], v[84:85], v[76:77], 1.0 op_sel_hi:[1,1,0]
	ds_read_b128 v[88:91], v141 offset:2192
	ds_read_b128 v[96:99], v141 offset:6288
	v_pk_mul_f32 v[84:85], v[92:93], v[76:77]
	v_mul_f32_e32 v76, 0x3f317217, v4
	v_fma_f32 v76, v4, s29, -v76
	v_fmac_f32_e32 v76, 0x3377d1cf, v4
	v_fmac_f32_e32 v76, 0x3f317217, v4
	v_cmp_lt_f32_e64 s[0:1], |v4|, s30
	v_add_f32_e32 v77, v82, v94
	v_mul_f32_e32 v77, 0xbfb8aa3b, v77
	v_cndmask_b32_e64 v4, v4, v76, s[0:1]
	v_cndmask_b32_e32 v76, 0, v205, vcc
	v_sub_f32_e32 v4, v4, v76
	v_add_f32_e32 v0, v0, v4
	v_add_f32_e32 v4, v243, v239
	v_mul_f32_e64 v76, |v4|, s27
	v_exp_f32_e32 v76, v76
	ds_read_b128 v[238:241], v200 offset:14400
	ds_read_b128 v[242:245], v200 offset:14464
	v_sub_f32_e32 v0, -0.5, v0
	v_add_f32_e32 v76, 1.0, v76
	v_cmp_gt_f32_e32 vcc, s28, v76
	v_mul_f32_e32 v0, 0x3fb8aa3b, v0
	v_exp_f32_e32 v0, v0
	v_cndmask_b32_e64 v82, 0, 32, vcc
	v_ldexp_f32 v76, v76, v82
	v_exp_f32_e32 v77, v77
	v_log_f32_e32 v76, v76
	s_waitcnt lgkmcnt(1)
	v_mfma_f32_16x16x32_bf16 v[12:15], v[238:241], v[12:15], 0
	v_xor_b32_e32 v82, 0x80000000, v0
	v_add_f32_e32 v0, 1.0, v77
	v_mul_f32_e32 v77, 0x3f317217, v76
	v_fma_f32 v77, v76, s29, -v77
	v_fmac_f32_e32 v77, 0x3377d1cf, v76
	s_waitcnt lgkmcnt(0)
	v_mfma_f32_16x16x32_bf16 v[12:15], v[242:245], v[28:31], v[12:15]
	ds_read_b128 v[28:31], v200 offset:5184
	ds_read_b128 v[242:245], v200 offset:5248
	v_fmac_f32_e32 v77, 0x3f317217, v76
	v_cmp_lt_f32_e64 s[0:1], |v76|, s30
	v_max_f32_e64 v4, -v4, 0
	s_waitcnt lgkmcnt(1)
	v_mfma_f32_16x16x32_bf16 v[8:11], v[28:31], v[8:11], 0
	v_cndmask_b32_e64 v76, v76, v77, s[0:1]
	v_cndmask_b32_e32 v77, 0, v205, vcc
	v_sub_f32_e32 v76, v76, v77
	v_add_f32_e32 v4, v4, v76
	v_add_f32_e32 v76, v83, v95
	v_mul_f32_e32 v76, 0xbfb8aa3b, v76
	v_exp_f32_e32 v77, v76
	v_sub_f32_e32 v4, -0.5, v4
	v_mul_f32_e32 v4, 0x3fb8aa3b, v4
	v_exp_f32_e32 v4, v4
	v_rcp_f32_e32 v76, v0
	v_add_f32_e32 v0, 1.0, v77
	v_rcp_f32_e32 v77, v0
	v_lshlrev_b32_e32 v0, 16, v1
	v_and_b32_e32 v1, 0xffff0000, v1
	v_xor_b32_e32 v83, 0x80000000, v4
	v_lshlrev_b32_e32 v4, 16, v5
	v_and_b32_e32 v5, 0xffff0000, v5
	v_cndmask_b32_e64 v1, v1, 0, s[2:3]
	v_cndmask_b32_e64 v0, v0, 0, s[2:3]
	s_waitcnt lgkmcnt(0)
	v_mfma_f32_16x16x32_bf16 v[16:19], v[242:245], v[16:19], v[8:11]
	v_add_f32_e64 v0, v0, -v4
	v_add_f32_e64 v1, v1, -v5
	ds_read_b128 v[238:241], v201 offset:28288
	v_pk_fma_f32 v[0:1], v[0:1], v[78:79], v[4:5]
	v_pk_add_f32 v[4:5], v[76:77], -1.0 op_sel_hi:[1,0]
	v_mfma_f32_16x16x32_bf16 v[20:23], v[246:249], v[20:23], 0
	v_fma_f32 v4, v86, v4, 1.0
	v_fma_f32 v5, v87, v5, 1.0
	ds_read_b128 v[8:11], v201 offset:28416
	v_pk_mul_f32 v[78:79], v[0:1], v[4:5]
	v_add_f32_e32 v4, v16, v52
	v_mul_f32_e64 v5, |v4|, s27
	v_exp_f32_e32 v5, v5
	v_max_f32_e64 v4, -v4, 0
	s_waitcnt lgkmcnt(1)
	v_mfma_f32_16x16x32_bf16 v[20:23], v[238:241], v[24:27], v[20:23]
	ds_read_b128 v[24:27], v201 offset:28352
	v_add_f32_e32 v5, 1.0, v5
	v_cmp_gt_f32_e32 vcc, s28, v5
	s_waitcnt lgkmcnt(0)
	v_mfma_f32_16x16x32_bf16 v[20:23], v[24:27], v[36:39], v[20:23]
	v_cndmask_b32_e64 v16, 0, 32, vcc
	v_ldexp_f32 v5, v5, v16
	v_log_f32_e32 v5, v5
	v_mfma_f32_16x16x32_bf16 v[8:11], v[8:11], v[32:35], v[20:23]
	v_cvt_pk_bf16_f32 v28, v237, v250
	v_cvt_pk_bf16_f32 v29, v82, v83
	v_mul_f32_e32 v16, 0x3f317217, v5
	v_fma_f32 v16, v5, s29, -v16
	v_fmac_f32_e32 v16, 0x3377d1cf, v5
	v_fmac_f32_e32 v16, 0x3f317217, v5
	v_cmp_lt_f32_e64 s[0:1], |v5|, s30
	ds_read_b128 v[20:23], v141 offset:4224
	ds_read_b128 v[24:27], v141 offset:4240
	v_cndmask_b32_e64 v5, v5, v16, s[0:1]
	v_cndmask_b32_e32 v16, 0, v205, vcc
	v_sub_f32_e32 v5, v5, v16
	v_add_f32_e32 v4, v4, v5
	v_sub_f32_e32 v4, -0.5, v4
	v_add_f32_e32 v5, v17, v53
	v_mul_f32_e32 v4, 0x3fb8aa3b, v4
	v_mul_f32_e64 v16, |v5|, s27
	v_exp_f32_e32 v4, v4
	v_exp_f32_e32 v16, v16
	v_max_f32_e64 v5, -v5, 0
	v_fmac_f32_e32 v220, v235, v59
	v_xor_b32_e32 v30, 0x80000000, v4
	v_add_f32_e32 v4, v12, v88
	v_add_f32_e32 v12, 1.0, v16
	v_cmp_gt_f32_e32 vcc, s28, v12
	v_mul_f32_e32 v4, 0xbfb8aa3b, v4
	v_exp_f32_e32 v4, v4
	v_cndmask_b32_e64 v16, 0, 32, vcc
	v_ldexp_f32 v12, v12, v16
	v_log_f32_e32 v12, v12
	v_add_f32_e32 v4, 1.0, v4
	v_rcp_f32_e32 v4, v4
	s_waitcnt lgkmcnt(1)
	v_pk_mul_f32 v[20:21], v[92:93], v[20:21]
	v_mul_f32_e32 v16, 0x3f317217, v12
	v_fma_f32 v16, v12, s29, -v16
	v_fmac_f32_e32 v16, 0x3377d1cf, v12
	v_fmac_f32_e32 v16, 0x3f317217, v12
	v_cmp_lt_f32_e64 s[0:1], |v12|, s30
	v_pk_mul_f32 v[22:23], v[0:1], v[22:23]
	v_cvt_pk_bf16_f32 v8, v8, v9
	v_cndmask_b32_e64 v12, v12, v16, s[0:1]
	v_cndmask_b32_e32 v16, 0, v205, vcc
	v_sub_f32_e32 v12, v12, v16
	v_add_f32_e32 v5, v5, v12
	v_sub_f32_e32 v5, -0.5, v5
	v_add_f32_e32 v12, v13, v89
	v_mul_f32_e32 v5, 0x3fb8aa3b, v5
	v_mul_f32_e32 v12, 0xbfb8aa3b, v12
	v_exp_f32_e32 v5, v5
	v_exp_f32_e32 v12, v12
	v_and_b32_e32 v13, 0xffff0000, v6
	v_cvt_pk_bf16_f32 v9, v10, v11
	v_xor_b32_e32 v31, 0x80000000, v5
	v_add_f32_e32 v5, 1.0, v12
	v_lshlrev_b32_e32 v12, 16, v6
	v_lshlrev_b32_e32 v6, 16, v2
	v_and_b32_e32 v2, 0xffff0000, v2
	v_cndmask_b32_e64 v17, v2, 0, s[2:3]
	v_add_f32_e32 v2, v18, v54
	v_mul_f32_e64 v16, |v2|, s27
	v_exp_f32_e32 v18, v16
	v_cndmask_b32_e64 v16, v6, 0, s[2:3]
	v_pk_add_f32 v[16:17], v[16:17], v[12:13] neg_lo:[0,1] neg_hi:[0,1]
	v_max_f32_e64 v2, -v2, 0
	v_add_f32_e32 v6, 1.0, v18
	v_cmp_gt_f32_e32 vcc, s28, v6
	v_pk_fma_f32 v[16:17], v[16:17], v[72:73], v[12:13]
	v_rcp_f32_e32 v5, v5
	v_cndmask_b32_e64 v12, 0, 32, vcc
	v_ldexp_f32 v6, v6, v12
	v_log_f32_e32 v6, v6
	v_pk_add_f32 v[12:13], v[4:5], -1.0 op_sel_hi:[1,0]
	v_cvt_pk_bf16_f32 v30, v30, v31
	v_pk_fma_f32 v[12:13], v[96:97], v[12:13], 1.0 op_sel_hi:[1,1,0]
	v_mul_f32_e32 v18, 0x3f317217, v6
	v_fma_f32 v18, v6, s29, -v18
	v_fmac_f32_e32 v18, 0x3377d1cf, v6
	v_fmac_f32_e32 v18, 0x3f317217, v6
	v_cmp_lt_f32_e64 s[0:1], |v6|, s30
	s_add_u32 s16, s16, 0x80
	s_addc_u32 s17, s17, 0
	v_cndmask_b32_e64 v6, v6, v18, s[0:1]
	v_cndmask_b32_e32 v18, 0, v205, vcc
	v_sub_f32_e32 v6, v6, v18
	v_add_f32_e32 v2, v2, v6
	v_add_f32_e32 v6, v19, v55
	v_mul_f32_e64 v18, |v6|, s27
	v_sub_f32_e32 v2, -0.5, v2
	v_exp_f32_e32 v32, v18
	v_mul_f32_e32 v2, 0x3fb8aa3b, v2
	v_exp_f32_e32 v2, v2
	v_pk_mul_f32 v[18:19], v[16:17], v[12:13]
	v_add_f32_e32 v13, 1.0, v32
	v_cmp_gt_f32_e32 vcc, s28, v13
	v_xor_b32_e32 v12, 0x80000000, v2
	v_add_f32_e32 v2, v14, v90
	v_cndmask_b32_e64 v14, 0, 32, vcc
	v_ldexp_f32 v13, v13, v14
	v_log_f32_e32 v13, v13
	v_max_f32_e64 v6, -v6, 0
	v_mul_f32_e32 v2, 0xbfb8aa3b, v2
	v_exp_f32_e32 v2, v2
	v_mul_f32_e32 v14, 0x3f317217, v13
	v_fma_f32 v14, v13, s29, -v14
	v_fmac_f32_e32 v14, 0x3377d1cf, v13
	v_fmac_f32_e32 v14, 0x3f317217, v13
	v_cmp_lt_f32_e64 s[0:1], |v13|, s30
	v_add_f32_e32 v2, 1.0, v2
	v_rcp_f32_e32 v32, v2
	v_cndmask_b32_e64 v13, v13, v14, s[0:1]
	v_cndmask_b32_e32 v14, 0, v205, vcc
	v_sub_f32_e32 v13, v13, v14
	v_add_f32_e32 v6, v6, v13
	v_add_f32_e32 v13, v15, v91
	v_mul_f32_e32 v13, 0xbfb8aa3b, v13
	v_exp_f32_e32 v13, v13
	v_sub_f32_e32 v6, -0.5, v6
	v_mul_f32_e32 v6, 0x3fb8aa3b, v6
	v_exp_f32_e32 v6, v6
	v_add_f32_e32 v2, 1.0, v13
	v_rcp_f32_e32 v33, v2
	v_lshlrev_b32_e32 v2, 16, v3
	v_and_b32_e32 v3, 0xffff0000, v3
	v_xor_b32_e32 v14, 0x80000000, v6
	v_lshlrev_b32_e32 v6, 16, v7
	v_and_b32_e32 v7, 0xffff0000, v7
	v_cndmask_b32_e64 v3, v3, 0, s[2:3]
	v_cndmask_b32_e64 v2, v2, 0, s[2:3]
	v_pk_add_f32 v[2:3], v[2:3], v[6:7] neg_lo:[0,1] neg_hi:[0,1]
	v_cvt_pk_bf16_f32 v31, v12, v14
	v_pk_fma_f32 v[2:3], v[2:3], v[74:75], v[6:7]
	v_pk_add_f32 v[6:7], v[32:33], -1.0 op_sel_hi:[1,0]
	global_store_dwordx4 v[114:115], v[28:31], off offset:64
	v_cvt_pk_bf16_f32 v12, v157, v206
	v_cvt_pk_bf16_f32 v13, v207, v209
	v_cvt_pk_bf16_f32 v14, v208, v210
	v_cvt_pk_bf16_f32 v15, v211, v212
	v_pk_mul_f32 v[28:29], v[176:177], v[40:41]
	v_pk_fma_f32 v[6:7], v[98:99], v[6:7], 1.0 op_sel_hi:[1,1,0]
	global_store_dwordx4 v[180:181], v[12:15], off offset:64
	v_mul_f32_e32 v30, v29, v29
	v_pk_mul_f32 v[6:7], v[2:3], v[6:7]
	v_cvt_pk_bf16_f32 v12, v213, v214
	v_cvt_pk_bf16_f32 v13, v215, v217
	v_cvt_pk_bf16_f32 v14, v216, v218
	v_cvt_pk_bf16_f32 v15, v219, v220
	global_store_dwordx4 v[184:185], v[12:15], off offset:64
	v_pk_fma_f32 v[30:31], v[28:29], v[28:29], v[30:31] op_sel_hi:[1,1,0]
	s_waitcnt lgkmcnt(0)
	v_pk_mul_f32 v[26:27], v[2:3], v[26:27]
	v_cvt_pk_bf16_f32 v14, v18, v19
	v_pk_mul_f32 v[18:19], v[178:179], v[42:43]
	v_cvt_pk_bf16_f32 v12, v84, v85
	v_cvt_pk_bf16_f32 v13, v78, v79
	v_cvt_pk_bf16_f32 v15, v6, v7
	v_pk_fma_f32 v[30:31], v[18:19], v[18:19], v[30:31]
	v_mul_f32_e32 v34, v19, v19
	global_store_dwordx4 v[186:187], v[12:15], off offset:64
	v_pk_add_f32 v[30:31], v[34:35], v[30:31] op_sel_hi:[0,1]
	v_mul_f32_e32 v2, v21, v21
	v_pk_mul_f32 v[14:15], v[182:183], v[44:45]
	v_pk_mul_f32 v[12:13], v[112:113], v[46:47]
	v_pk_fma_f32 v[30:31], v[14:15], v[14:15], v[30:31]
	v_mul_f32_e32 v34, v15, v15
	v_pk_add_f32 v[30:31], v[34:35], v[30:31] op_sel_hi:[0,1]
	v_pk_fma_f32 v[30:31], v[12:13], v[12:13], v[30:31]
	v_mul_f32_e32 v34, v13, v13
	v_pk_add_f32 v[30:31], v[34:35], v[30:31] op_sel_hi:[0,1]
	v_pk_fma_f32 v[0:1], v[20:21], v[20:21], v[30:31]
	v_pk_mul_f32 v[16:17], v[16:17], v[24:25]
	v_pk_add_f32 v[0:1], v[2:3], v[0:1] op_sel_hi:[0,1]
	v_pk_fma_f32 v[0:1], v[22:23], v[22:23], v[0:1]
	v_mul_f32_e32 v2, v23, v23
	v_pk_add_f32 v[0:1], v[2:3], v[0:1] op_sel_hi:[0,1]
	v_pk_fma_f32 v[0:1], v[16:17], v[16:17], v[0:1]
	v_mul_f32_e32 v2, v17, v17
	v_pk_add_f32 v[0:1], v[2:3], v[0:1] op_sel_hi:[0,1]
	v_pk_fma_f32 v[0:1], v[26:27], v[26:27], v[0:1]
	v_mul_f32_e32 v2, v27, v27
	v_pk_add_f32 v[0:1], v[2:3], v[0:1] op_sel_hi:[0,1]
	v_mov_b32_e32 v1, v0
	s_nop 1
	v_permlane16_swap_b32_e32 v0, v1
	v_add_f32_e32 v0, v0, v1
	v_mov_b32_e32 v1, v0
	s_nop 1
	v_permlane32_swap_b32_e32 v0, v1
	v_add_f32_e32 v0, v0, v1
	v_max_f32_e32 v0, 0x2b8cbccc, v0
	v_rsq_f32_e32 v24, v0
	v_cvt_pk_bf16_f32 v6, v48, v49
	v_cvt_pk_bf16_f32 v7, v50, v51
	global_store_dwordx4 v[102:103], v[6:9], off offset:64
	v_pk_mul_f32 v[0:1], v[28:29], v[24:25] op_sel_hi:[1,0]
	v_pk_mul_f32 v[10:11], v[18:19], v[24:25] op_sel_hi:[1,0]
	v_pk_mul_f32 v[2:3], v[14:15], v[24:25] op_sel_hi:[1,0]
	v_pk_mul_f32 v[6:7], v[108:109], v[0:1]
	v_pk_mul_f32 v[12:13], v[12:13], v[24:25] op_sel_hi:[1,0]
	v_pk_mul_f32 v[14:15], v[110:111], v[10:11]
	v_cvt_pk_bf16_f32 v0, v0, v1
	v_cvt_pk_bf16_f32 v1, v10, v11
	v_add_co_u32_e32 v10, vcc, s38, v100
	v_pk_mul_f32 v[8:9], v[104:105], v[2:3]
	v_cvt_pk_bf16_f32 v2, v2, v3
	v_cvt_pk_bf16_f32 v3, v12, v13
	v_addc_co_u32_e32 v11, vcc, 0, v101, vcc
	v_pk_mul_f32 v[18:19], v[106:107], v[12:13]
	global_store_dwordx4 v[10:11], v[0:3], off
	v_pk_mul_f32 v[12:13], v[22:23], v[24:25] op_sel_hi:[1,0]
	s_cmpk_lg_i32 s16, 0x400
	v_cvt_pk_bf16_f32 v0, v6, v7
	v_add_co_u32_e32 v6, vcc, s39, v100
	v_cvt_pk_bf16_f32 v1, v14, v15
	v_cvt_pk_bf16_f32 v2, v8, v9
	v_cvt_pk_bf16_f32 v3, v18, v19
	v_addc_co_u32_e32 v7, vcc, 0, v101, vcc
	global_store_dwordx4 v[6:7], v[0:3], off
	v_pk_mul_f32 v[14:15], v[26:27], v[24:25] op_sel_hi:[1,0]
	v_add_u32_e32 v141, 0x100, v141
	v_pk_mul_f32 v[0:1], v[20:21], v[24:25] op_sel_hi:[1,0]
	v_pk_mul_f32 v[2:3], v[16:17], v[24:25] op_sel_hi:[1,0]
	v_pk_mul_f32 v[8:9], v[80:81], v[0:1]
	v_pk_mul_f32 v[4:5], v[4:5], v[2:3]
	v_pk_mul_f32 v[16:17], v[76:77], v[12:13]
	v_pk_mul_f32 v[18:19], v[32:33], v[14:15]
	v_cvt_pk_bf16_f32 v0, v0, v1
	v_cvt_pk_bf16_f32 v1, v12, v13
	v_cvt_pk_bf16_f32 v2, v2, v3
	v_cvt_pk_bf16_f32 v3, v14, v15
	global_store_dwordx4 v[10:11], v[0:3], off offset:64
	s_nop 1
	v_cvt_pk_bf16_f32 v0, v8, v9
	v_cvt_pk_bf16_f32 v1, v16, v17
	v_cvt_pk_bf16_f32 v2, v4, v5
	v_cvt_pk_bf16_f32 v3, v18, v19
	global_store_dwordx4 v[6:7], v[0:3], off offset:64
	s_cbranch_scc0 .LBB0_1753
.LBB0_1770:
	s_nop 0
	v_lshl_add_u64 v[0:1], v[158:159], 0, s[16:17]
	v_add_co_u32_e32 v8, vcc, 0x7000000, v0
	v_lshl_add_u64 v[24:25], v[164:165], 0, s[16:17]
	s_nop 0
	v_addc_co_u32_e32 v9, vcc, 0, v1, vcc
	global_load_dwordx4 v[20:23], v[8:9], off
	global_load_dwordx4 v[60:63], v[8:9], off offset:64
	global_load_dwordx4 v[16:19], v[24:25], off offset:-1088
	global_load_dwordx4 v[56:59], v[24:25], off offset:-1024
	global_load_dwordx4 v[68:71], v[8:9], off offset:1024
	global_load_dwordx4 v[4:7], v[8:9], off offset:1088
	global_load_dwordx4 v[64:67], v[24:25], off offset:-64
	global_load_dwordx4 v[0:3], v[24:25], off
	global_load_dwordx4 v[12:15], v[8:9], off offset:2048
	global_load_dwordx4 v[52:55], v[8:9], off offset:2112
	s_nop 0
	global_load_dwordx4 v[8:11], v[24:25], off offset:960
	global_load_dwordx4 v[48:51], v[24:25], off offset:1024
	s_waitcnt lgkmcnt(0)
	s_barrier
	v_lshl_add_u64 v[24:25], s[96:97], 0, v[174:175]
	v_add_co_u32_e32 v26, vcc, 0x2900000, v24
	s_nop 1
	v_addc_co_u32_e32 v27, vcc, 0, v25, vcc
	global_load_dwordx4 v[208:211], v[26:27], off
	v_add_co_u32_e32 v24, vcc, 0x2910000, v24
	s_nop 1
	v_addc_co_u32_e32 v25, vcc, 0, v25, vcc
	global_load_dwordx4 v[212:215], v[24:25], off
	v_lshl_add_u64 v[24:25], s[96:97], 0, v[170:171]
	v_lshl_add_u64 v[28:29], s[96:97], 0, v[172:173]
	global_load_dwordx4 v[24:27], v[24:25], off
	s_nop 0
	global_load_dwordx4 v[28:31], v[28:29], off
	s_waitcnt vmcnt(2)
	ds_write_b128 v195, v[208:211]
	ds_write_b128 v197, v[212:215] offset:9216
	s_nop 1
	s_branch .Lprep_rest
